# 7.11 back-edge rotation: K-loop counter update / exit test moved in front of the loop-back barrier
# baseline (speedup 1.0000x reference)
.LBB0_24:
	ds_read_b128 v[154:157], v138
	ds_read_b128 v[158:161], v139
	ds_read_b128 v[162:165], v140
	ds_read_b128 v[194:197], v141
	ds_read_b128 v[198:201], v142
	ds_read_b128 v[202:205], v143
	ds_read_b128 v[206:209], v144
	ds_read_b128 v[210:213], v145
	s_add_u32 s14, s96, s88
	s_addc_u32 s15, s97, s89
	s_add_u32 s14, s14, 0x4000900
	s_addc_u32 s15, s15, 0
	s_add_u32 s36, s42, s88
	s_addc_u32 s37, s43, s89
	s_cmpk_eq_i32 s88, 0x700
	s_cselect_b32 s27, s87, s15
	s_cselect_b32 s26, s86, s14
	s_cselect_b32 s15, s85, s37
	s_cselect_b32 s14, s84, s36
	v_lshl_add_u64 v[166:167], v[130:131], 0, s[88:89]
	s_add_i32 m0, s94, 0xc000
	ds_read_b128 v[214:217], v137
	ds_read_b128 v[218:221], v137 offset:1024
	ds_read_b128 v[222:225], v137 offset:2048
	ds_read_b128 v[226:229], v137 offset:3072
	ds_read_b128 v[230:233], v137 offset:4096
	ds_read_b128 v[234:237], v137 offset:5120
	ds_read_b128 v[238:241], v137 offset:6144
	ds_read_b128 v[242:245], v137 offset:7168
	global_load_lds_dwordx4 v[166:167], off
	v_lshl_add_u64 v[166:167], v[132:133], 0, s[88:89]
	s_mov_b32 m0, s48
	s_nop 0
	global_load_lds_dwordx4 v[166:167], off
	s_waitcnt vmcnt(8)
	s_waitcnt lgkmcnt(0)
	s_barrier
	s_setprio 1
	s_waitcnt lgkmcnt(0)
	v_mfma_f32_16x16x32_bf16 v[124:127], v[154:157], v[214:217], v[124:127]
	v_mfma_f32_16x16x32_bf16 v[120:123], v[162:165], v[214:217], v[120:123]
	v_mfma_f32_16x16x32_bf16 v[116:119], v[154:157], v[222:225], v[116:119]
	v_mfma_f32_16x16x32_bf16 v[112:115], v[162:165], v[222:225], v[112:115]
	v_mfma_f32_16x16x32_bf16 v[108:111], v[154:157], v[230:233], v[108:111]
	v_mfma_f32_16x16x32_bf16 v[104:107], v[162:165], v[230:233], v[104:107]
	v_mfma_f32_16x16x32_bf16 v[76:79], v[154:157], v[238:241], v[76:79]
	v_mfma_f32_16x16x32_bf16 v[72:75], v[162:165], v[238:241], v[72:75]
	v_mfma_f32_16x16x32_bf16 v[124:127], v[158:161], v[218:221], v[124:127]
	v_mfma_f32_16x16x32_bf16 v[120:123], v[194:197], v[218:221], v[120:123]
	v_mfma_f32_16x16x32_bf16 v[116:119], v[158:161], v[226:229], v[116:119]
	v_mfma_f32_16x16x32_bf16 v[112:115], v[194:197], v[226:229], v[112:115]
	v_mfma_f32_16x16x32_bf16 v[108:111], v[158:161], v[234:237], v[108:111]
	v_mfma_f32_16x16x32_bf16 v[104:107], v[194:197], v[234:237], v[104:107]
	v_mfma_f32_16x16x32_bf16 v[76:79], v[158:161], v[242:245], v[76:79]
	v_mfma_f32_16x16x32_bf16 v[72:75], v[194:197], v[242:245], v[72:75]
	s_setprio 0
	s_setprio 1
	v_mfma_f32_16x16x32_bf16 v[100:103], v[198:201], v[214:217], v[100:103]
	v_mfma_f32_16x16x32_bf16 v[96:99], v[206:209], v[214:217], v[96:99]
	v_mfma_f32_16x16x32_bf16 v[92:95], v[198:201], v[222:225], v[92:95]
	v_mfma_f32_16x16x32_bf16 v[88:91], v[206:209], v[222:225], v[88:91]
	v_mfma_f32_16x16x32_bf16 v[84:87], v[198:201], v[230:233], v[84:87]
	v_mfma_f32_16x16x32_bf16 v[80:83], v[206:209], v[230:233], v[80:83]
	v_mfma_f32_16x16x32_bf16 v[52:55], v[198:201], v[238:241], v[52:55]
	v_mfma_f32_16x16x32_bf16 v[44:47], v[206:209], v[238:241], v[44:47]
	v_mfma_f32_16x16x32_bf16 v[100:103], v[202:205], v[218:221], v[100:103]
	v_mfma_f32_16x16x32_bf16 v[96:99], v[210:213], v[218:221], v[96:99]
	v_mfma_f32_16x16x32_bf16 v[92:95], v[202:205], v[226:229], v[92:95]
	v_mfma_f32_16x16x32_bf16 v[88:91], v[210:213], v[226:229], v[88:91]
	v_mfma_f32_16x16x32_bf16 v[84:87], v[202:205], v[234:237], v[84:87]
	v_mfma_f32_16x16x32_bf16 v[80:83], v[210:213], v[234:237], v[80:83]
	v_mfma_f32_16x16x32_bf16 v[52:55], v[202:205], v[242:245], v[52:55]
	v_mfma_f32_16x16x32_bf16 v[44:47], v[210:213], v[242:245], v[44:47]
	s_setprio 0
	s_barrier
	s_mov_b32 m0, s41
	v_lshl_add_u64 v[166:167], s[14:15], 0, v[168:169]
	s_add_u32 s36, s14, 0x40000
	ds_read_b128 v[214:217], v137 offset:16384
	ds_read_b128 v[218:221], v137 offset:17408
	ds_read_b128 v[222:225], v137 offset:18432
	ds_read_b128 v[226:229], v137 offset:19456
	ds_read_b128 v[230:233], v137 offset:20480
	ds_read_b128 v[234:237], v137 offset:21504
	ds_read_b128 v[238:241], v137 offset:22528
	ds_read_b128 v[242:245], v137 offset:23552
	global_load_lds_dwordx4 v[166:167], off
	v_lshl_add_u64 v[246:247], s[14:15], 0, v[128:129]
	s_mov_b32 m0, s59
	s_addc_u32 s37, s15, 0
	global_load_lds_dwordx4 v[246:247], off
	v_lshl_add_u64 v[248:249], s[36:37], 0, v[168:169]
	s_mov_b32 m0, s95
	v_lshl_add_u64 v[250:251], s[26:27], 0, v[128:129]
	global_load_lds_dwordx4 v[248:249], off
	v_lshl_add_u64 v[248:249], s[36:37], 0, v[128:129]
	s_mov_b32 m0, vcc_lo
	s_nop 0
	global_load_lds_dwordx4 v[248:249], off
	v_lshl_add_u64 v[248:249], s[26:27], 0, v[168:169]
	s_mov_b32 m0, s94
	s_nop 0
	global_load_lds_dwordx4 v[248:249], off
	s_mov_b32 m0, vcc_hi
	s_nop 0
	global_load_lds_dwordx4 v[250:251], off
	s_waitcnt vmcnt(8)
	s_waitcnt lgkmcnt(0)
	s_barrier
	s_setprio 1
	s_waitcnt lgkmcnt(0)
	v_mfma_f32_16x16x32_bf16 v[68:71], v[154:157], v[214:217], v[68:71]
	v_mfma_f32_16x16x32_bf16 v[64:67], v[162:165], v[214:217], v[64:67]
	v_mfma_f32_16x16x32_bf16 v[60:63], v[154:157], v[222:225], v[60:63]
	v_mfma_f32_16x16x32_bf16 v[56:59], v[162:165], v[222:225], v[56:59]
	v_mfma_f32_16x16x32_bf16 v[48:51], v[154:157], v[230:233], v[48:51]
	v_mfma_f32_16x16x32_bf16 v[40:43], v[162:165], v[230:233], v[40:43]
	v_mfma_f32_16x16x32_bf16 v[36:39], v[154:157], v[238:241], v[36:39]
	v_mfma_f32_16x16x32_bf16 v[32:35], v[162:165], v[238:241], v[32:35]
	v_mfma_f32_16x16x32_bf16 v[68:71], v[158:161], v[218:221], v[68:71]
	v_mfma_f32_16x16x32_bf16 v[64:67], v[194:197], v[218:221], v[64:67]
	v_mfma_f32_16x16x32_bf16 v[60:63], v[158:161], v[226:229], v[60:63]
	v_mfma_f32_16x16x32_bf16 v[56:59], v[194:197], v[226:229], v[56:59]
	v_mfma_f32_16x16x32_bf16 v[48:51], v[158:161], v[234:237], v[48:51]
	v_mfma_f32_16x16x32_bf16 v[40:43], v[194:197], v[234:237], v[40:43]
	v_mfma_f32_16x16x32_bf16 v[36:39], v[158:161], v[242:245], v[36:39]
	v_mfma_f32_16x16x32_bf16 v[32:35], v[194:197], v[242:245], v[32:35]
	s_setprio 0
	s_setprio 1
	v_mfma_f32_16x16x32_bf16 v[28:31], v[198:201], v[214:217], v[28:31]
	v_mfma_f32_16x16x32_bf16 v[24:27], v[206:209], v[214:217], v[24:27]
	v_mfma_f32_16x16x32_bf16 v[20:23], v[198:201], v[222:225], v[20:23]
	v_mfma_f32_16x16x32_bf16 v[16:19], v[206:209], v[222:225], v[16:19]
	v_mfma_f32_16x16x32_bf16 v[12:15], v[198:201], v[230:233], v[12:15]
	v_mfma_f32_16x16x32_bf16 v[8:11], v[206:209], v[230:233], v[8:11]
	v_mfma_f32_16x16x32_bf16 v[4:7], v[198:201], v[238:241], v[4:7]
	v_mfma_f32_16x16x32_bf16 v[0:3], v[206:209], v[238:241], v[0:3]
	v_mfma_f32_16x16x32_bf16 v[28:31], v[202:205], v[218:221], v[28:31]
	v_mfma_f32_16x16x32_bf16 v[24:27], v[210:213], v[218:221], v[24:27]
	v_mfma_f32_16x16x32_bf16 v[20:23], v[202:205], v[226:229], v[20:23]
	v_mfma_f32_16x16x32_bf16 v[16:19], v[210:213], v[226:229], v[16:19]
	v_mfma_f32_16x16x32_bf16 v[12:15], v[202:205], v[234:237], v[12:15]
	v_mfma_f32_16x16x32_bf16 v[8:11], v[210:213], v[234:237], v[8:11]
	v_mfma_f32_16x16x32_bf16 v[4:7], v[202:205], v[242:245], v[4:7]
	v_mfma_f32_16x16x32_bf16 v[0:3], v[210:213], v[242:245], v[0:3]
	s_setprio 0
	s_barrier
	ds_read_b128 v[154:157], v146
	ds_read_b128 v[158:161], v147
	ds_read_b128 v[162:165], v148
	ds_read_b128 v[194:197], v149
	ds_read_b128 v[198:201], v150
	ds_read_b128 v[202:205], v151
	ds_read_b128 v[206:209], v152
	ds_read_b128 v[210:213], v153
	s_add_u32 s26, s26, 0x40000
	s_addc_u32 s27, s27, 0
	s_mov_b32 m0, s28
	v_lshl_add_u64 v[180:181], s[26:27], 0, v[168:169]
	ds_read_b128 v[214:217], v137 offset:32768
	ds_read_b128 v[218:221], v137 offset:33792
	ds_read_b128 v[222:225], v137 offset:34816
	ds_read_b128 v[226:229], v137 offset:35840
	ds_read_b128 v[230:233], v137 offset:36864
	ds_read_b128 v[234:237], v137 offset:37888
	ds_read_b128 v[238:241], v137 offset:38912
	ds_read_b128 v[242:245], v137 offset:39936
	global_load_lds_dwordx4 v[180:181], off
	v_lshl_add_u64 v[180:181], s[26:27], 0, v[128:129]
	s_mov_b32 m0, s29
	s_nop 0
	global_load_lds_dwordx4 v[180:181], off
	s_waitcnt vmcnt(8)
	s_waitcnt lgkmcnt(0)
	s_barrier
	s_setprio 1
	s_waitcnt lgkmcnt(0)
	v_mfma_f32_16x16x32_bf16 v[124:127], v[154:157], v[214:217], v[124:127]
	v_mfma_f32_16x16x32_bf16 v[120:123], v[162:165], v[214:217], v[120:123]
	v_mfma_f32_16x16x32_bf16 v[116:119], v[154:157], v[222:225], v[116:119]
	v_mfma_f32_16x16x32_bf16 v[112:115], v[162:165], v[222:225], v[112:115]
	v_mfma_f32_16x16x32_bf16 v[108:111], v[154:157], v[230:233], v[108:111]
	v_mfma_f32_16x16x32_bf16 v[104:107], v[162:165], v[230:233], v[104:107]
	v_mfma_f32_16x16x32_bf16 v[76:79], v[154:157], v[238:241], v[76:79]
	v_mfma_f32_16x16x32_bf16 v[72:75], v[162:165], v[238:241], v[72:75]
	v_mfma_f32_16x16x32_bf16 v[124:127], v[158:161], v[218:221], v[124:127]
	v_mfma_f32_16x16x32_bf16 v[120:123], v[194:197], v[218:221], v[120:123]
	v_mfma_f32_16x16x32_bf16 v[116:119], v[158:161], v[226:229], v[116:119]
	v_mfma_f32_16x16x32_bf16 v[112:115], v[194:197], v[226:229], v[112:115]
	v_mfma_f32_16x16x32_bf16 v[108:111], v[158:161], v[234:237], v[108:111]
	v_mfma_f32_16x16x32_bf16 v[104:107], v[194:197], v[234:237], v[104:107]
	v_mfma_f32_16x16x32_bf16 v[76:79], v[158:161], v[242:245], v[76:79]
	v_mfma_f32_16x16x32_bf16 v[72:75], v[194:197], v[242:245], v[72:75]
	s_setprio 0
	s_setprio 1
	v_mfma_f32_16x16x32_bf16 v[100:103], v[198:201], v[214:217], v[100:103]
	v_mfma_f32_16x16x32_bf16 v[96:99], v[206:209], v[214:217], v[96:99]
	v_mfma_f32_16x16x32_bf16 v[92:95], v[198:201], v[222:225], v[92:95]
	v_mfma_f32_16x16x32_bf16 v[88:91], v[206:209], v[222:225], v[88:91]
	v_mfma_f32_16x16x32_bf16 v[84:87], v[198:201], v[230:233], v[84:87]
	v_mfma_f32_16x16x32_bf16 v[80:83], v[206:209], v[230:233], v[80:83]
	v_mfma_f32_16x16x32_bf16 v[52:55], v[198:201], v[238:241], v[52:55]
	v_mfma_f32_16x16x32_bf16 v[44:47], v[206:209], v[238:241], v[44:47]
	v_mfma_f32_16x16x32_bf16 v[100:103], v[202:205], v[218:221], v[100:103]
	v_mfma_f32_16x16x32_bf16 v[96:99], v[210:213], v[218:221], v[96:99]
	v_mfma_f32_16x16x32_bf16 v[92:95], v[202:205], v[226:229], v[92:95]
	v_mfma_f32_16x16x32_bf16 v[88:91], v[210:213], v[226:229], v[88:91]
	v_mfma_f32_16x16x32_bf16 v[84:87], v[202:205], v[234:237], v[84:87]
	v_mfma_f32_16x16x32_bf16 v[80:83], v[210:213], v[234:237], v[80:83]
	v_mfma_f32_16x16x32_bf16 v[52:55], v[202:205], v[242:245], v[52:55]
	v_mfma_f32_16x16x32_bf16 v[44:47], v[210:213], v[242:245], v[44:47]
	s_setprio 0
	s_barrier
	s_mov_b32 m0, s19
	v_lshl_add_u64 v[166:167], v[166:167], 0, s[34:35]
	s_add_u32 s14, s14, 0x40080
	ds_read_b128 v[214:217], v137 offset:49152
	ds_read_b128 v[218:221], v137 offset:50176
	ds_read_b128 v[222:225], v137 offset:51200
	ds_read_b128 v[226:229], v137 offset:52224
	ds_read_b128 v[230:233], v137 offset:53248
	ds_read_b128 v[234:237], v137 offset:54272
	ds_read_b128 v[238:241], v137 offset:55296
	ds_read_b128 v[242:245], v137 offset:56320
	global_load_lds_dwordx4 v[166:167], off
	v_lshl_add_u64 v[166:167], v[246:247], 0, s[34:35]
	s_mov_b32 m0, s30
	s_addc_u32 s15, s15, 0
	global_load_lds_dwordx4 v[166:167], off
	v_lshl_add_u64 v[166:167], s[14:15], 0, v[168:169]
	s_mov_b32 m0, s63
	s_nop 0
	global_load_lds_dwordx4 v[166:167], off
	v_lshl_add_u64 v[166:167], s[14:15], 0, v[128:129]
	s_mov_b32 m0, s24
	s_nop 0
	global_load_lds_dwordx4 v[166:167], off
	v_lshl_add_u64 v[166:167], v[248:249], 0, s[34:35]
	s_mov_b32 m0, s61
	s_nop 0
	global_load_lds_dwordx4 v[166:167], off
	v_lshl_add_u64 v[166:167], v[250:251], 0, s[34:35]
	s_mov_b32 m0, s62
	s_nop 0
	global_load_lds_dwordx4 v[166:167], off
	s_waitcnt vmcnt(8)
	s_waitcnt lgkmcnt(0)
	s_barrier
	s_setprio 1
	s_waitcnt lgkmcnt(0)
	v_mfma_f32_16x16x32_bf16 v[68:71], v[154:157], v[214:217], v[68:71]
	v_mfma_f32_16x16x32_bf16 v[64:67], v[162:165], v[214:217], v[64:67]
	v_mfma_f32_16x16x32_bf16 v[60:63], v[154:157], v[222:225], v[60:63]
	v_mfma_f32_16x16x32_bf16 v[56:59], v[162:165], v[222:225], v[56:59]
	v_mfma_f32_16x16x32_bf16 v[48:51], v[154:157], v[230:233], v[48:51]
	v_mfma_f32_16x16x32_bf16 v[40:43], v[162:165], v[230:233], v[40:43]
	v_mfma_f32_16x16x32_bf16 v[36:39], v[154:157], v[238:241], v[36:39]
	v_mfma_f32_16x16x32_bf16 v[32:35], v[162:165], v[238:241], v[32:35]
	v_mfma_f32_16x16x32_bf16 v[68:71], v[158:161], v[218:221], v[68:71]
	v_mfma_f32_16x16x32_bf16 v[64:67], v[194:197], v[218:221], v[64:67]
	v_mfma_f32_16x16x32_bf16 v[60:63], v[158:161], v[226:229], v[60:63]
	v_mfma_f32_16x16x32_bf16 v[56:59], v[194:197], v[226:229], v[56:59]
	v_mfma_f32_16x16x32_bf16 v[48:51], v[158:161], v[234:237], v[48:51]
	v_mfma_f32_16x16x32_bf16 v[40:43], v[194:197], v[234:237], v[40:43]
	v_mfma_f32_16x16x32_bf16 v[36:39], v[158:161], v[242:245], v[36:39]
	v_mfma_f32_16x16x32_bf16 v[32:35], v[194:197], v[242:245], v[32:35]
	s_setprio 0
	s_setprio 1
	v_mfma_f32_16x16x32_bf16 v[28:31], v[198:201], v[214:217], v[28:31]
	v_mfma_f32_16x16x32_bf16 v[24:27], v[206:209], v[214:217], v[24:27]
	v_mfma_f32_16x16x32_bf16 v[20:23], v[198:201], v[222:225], v[20:23]
	v_mfma_f32_16x16x32_bf16 v[16:19], v[206:209], v[222:225], v[16:19]
	v_mfma_f32_16x16x32_bf16 v[12:15], v[198:201], v[230:233], v[12:15]
	v_mfma_f32_16x16x32_bf16 v[8:11], v[206:209], v[230:233], v[8:11]
	v_mfma_f32_16x16x32_bf16 v[4:7], v[198:201], v[238:241], v[4:7]
	v_mfma_f32_16x16x32_bf16 v[0:3], v[206:209], v[238:241], v[0:3]
	v_mfma_f32_16x16x32_bf16 v[28:31], v[202:205], v[218:221], v[28:31]
	v_mfma_f32_16x16x32_bf16 v[24:27], v[210:213], v[218:221], v[24:27]
	v_mfma_f32_16x16x32_bf16 v[20:23], v[202:205], v[226:229], v[20:23]
	v_mfma_f32_16x16x32_bf16 v[16:19], v[210:213], v[226:229], v[16:19]
	v_mfma_f32_16x16x32_bf16 v[12:15], v[202:205], v[234:237], v[12:15]
	v_mfma_f32_16x16x32_bf16 v[8:11], v[210:213], v[234:237], v[8:11]
	v_mfma_f32_16x16x32_bf16 v[4:7], v[202:205], v[242:245], v[4:7]
	v_mfma_f32_16x16x32_bf16 v[0:3], v[210:213], v[242:245], v[0:3]
	s_setprio 0
	s_add_i32 s60, s60, 2
	s_add_u32 s88, s88, 0x100
	s_addc_u32 s89, s89, 0
	s_cmp_lt_u32 s60, 12
	s_barrier
	s_cbranch_scc1 .LBB0_24
	ds_read_b128 v[154:157], v138
	ds_read_b128 v[158:161], v139
	ds_read_b128 v[162:165], v140
	ds_read_b128 v[194:197], v141
	ds_read_b128 v[198:201], v142
	ds_read_b128 v[202:205], v143
	ds_read_b128 v[206:209], v144
	ds_read_b128 v[210:213], v145
	s_add_u32 s14, s96, s88
	s_addc_u32 s15, s97, s89
	s_add_u32 s14, s14, 0x4000900
	s_addc_u32 s15, s15, 0
	s_add_u32 s36, s42, s88
	s_addc_u32 s37, s43, s89
	s_cmpk_eq_i32 s88, 0x700
	s_cselect_b32 s27, s87, s15
	s_cselect_b32 s26, s86, s14
	s_cselect_b32 s15, s85, s37
	s_cselect_b32 s14, s84, s36
	v_lshl_add_u64 v[166:167], v[130:131], 0, s[88:89]
	s_add_i32 m0, s94, 0xc000
	ds_read_b128 v[214:217], v137
	ds_read_b128 v[218:221], v137 offset:1024
	ds_read_b128 v[222:225], v137 offset:2048
	ds_read_b128 v[226:229], v137 offset:3072
	ds_read_b128 v[230:233], v137 offset:4096
	ds_read_b128 v[234:237], v137 offset:5120
	ds_read_b128 v[238:241], v137 offset:6144
	ds_read_b128 v[242:245], v137 offset:7168
	global_load_lds_dwordx4 v[166:167], off
	v_lshl_add_u64 v[166:167], v[132:133], 0, s[88:89]
	s_mov_b32 m0, s48
	s_nop 0
	global_load_lds_dwordx4 v[166:167], off
	s_waitcnt vmcnt(8)
	s_waitcnt lgkmcnt(0)
	s_barrier
	s_setprio 1
	s_waitcnt lgkmcnt(0)
	v_mfma_f32_16x16x32_bf16 v[124:127], v[154:157], v[214:217], v[124:127]
	v_mfma_f32_16x16x32_bf16 v[120:123], v[162:165], v[214:217], v[120:123]
	v_mfma_f32_16x16x32_bf16 v[116:119], v[154:157], v[222:225], v[116:119]
	v_mfma_f32_16x16x32_bf16 v[112:115], v[162:165], v[222:225], v[112:115]
	v_mfma_f32_16x16x32_bf16 v[108:111], v[154:157], v[230:233], v[108:111]
	v_mfma_f32_16x16x32_bf16 v[104:107], v[162:165], v[230:233], v[104:107]
	v_mfma_f32_16x16x32_bf16 v[76:79], v[154:157], v[238:241], v[76:79]
	v_mfma_f32_16x16x32_bf16 v[72:75], v[162:165], v[238:241], v[72:75]
	v_mfma_f32_16x16x32_bf16 v[124:127], v[158:161], v[218:221], v[124:127]
	v_mfma_f32_16x16x32_bf16 v[120:123], v[194:197], v[218:221], v[120:123]
	v_mfma_f32_16x16x32_bf16 v[116:119], v[158:161], v[226:229], v[116:119]
	v_mfma_f32_16x16x32_bf16 v[112:115], v[194:197], v[226:229], v[112:115]
	v_mfma_f32_16x16x32_bf16 v[108:111], v[158:161], v[234:237], v[108:111]
	v_mfma_f32_16x16x32_bf16 v[104:107], v[194:197], v[234:237], v[104:107]
	v_mfma_f32_16x16x32_bf16 v[76:79], v[158:161], v[242:245], v[76:79]
	v_mfma_f32_16x16x32_bf16 v[72:75], v[194:197], v[242:245], v[72:75]
	s_setprio 0
	s_setprio 1
	v_mfma_f32_16x16x32_bf16 v[100:103], v[198:201], v[214:217], v[100:103]
	v_mfma_f32_16x16x32_bf16 v[96:99], v[206:209], v[214:217], v[96:99]
	v_mfma_f32_16x16x32_bf16 v[92:95], v[198:201], v[222:225], v[92:95]
	v_mfma_f32_16x16x32_bf16 v[88:91], v[206:209], v[222:225], v[88:91]
	v_mfma_f32_16x16x32_bf16 v[84:87], v[198:201], v[230:233], v[84:87]
	v_mfma_f32_16x16x32_bf16 v[80:83], v[206:209], v[230:233], v[80:83]
	v_mfma_f32_16x16x32_bf16 v[52:55], v[198:201], v[238:241], v[52:55]
	v_mfma_f32_16x16x32_bf16 v[44:47], v[206:209], v[238:241], v[44:47]
	v_mfma_f32_16x16x32_bf16 v[100:103], v[202:205], v[218:221], v[100:103]
	v_mfma_f32_16x16x32_bf16 v[96:99], v[210:213], v[218:221], v[96:99]
	v_mfma_f32_16x16x32_bf16 v[92:95], v[202:205], v[226:229], v[92:95]
	v_mfma_f32_16x16x32_bf16 v[88:91], v[210:213], v[226:229], v[88:91]
	v_mfma_f32_16x16x32_bf16 v[84:87], v[202:205], v[234:237], v[84:87]
	v_mfma_f32_16x16x32_bf16 v[80:83], v[210:213], v[234:237], v[80:83]
	v_mfma_f32_16x16x32_bf16 v[52:55], v[202:205], v[242:245], v[52:55]
	v_mfma_f32_16x16x32_bf16 v[44:47], v[210:213], v[242:245], v[44:47]
	s_setprio 0
	s_barrier
	s_mov_b32 m0, s41
	v_lshl_add_u64 v[166:167], s[14:15], 0, v[168:169]
	s_add_u32 s36, s14, 0x40000
	ds_read_b128 v[214:217], v137 offset:16384
	ds_read_b128 v[218:221], v137 offset:17408
	ds_read_b128 v[222:225], v137 offset:18432
	ds_read_b128 v[226:229], v137 offset:19456
	ds_read_b128 v[230:233], v137 offset:20480
	ds_read_b128 v[234:237], v137 offset:21504
	ds_read_b128 v[238:241], v137 offset:22528
	ds_read_b128 v[242:245], v137 offset:23552
	v_lshl_add_u64 v[246:247], s[14:15], 0, v[128:129]
	s_mov_b32 m0, s59
	s_addc_u32 s37, s15, 0
	v_lshl_add_u64 v[248:249], s[36:37], 0, v[168:169]
	s_mov_b32 m0, s95
	v_lshl_add_u64 v[250:251], s[26:27], 0, v[128:129]
	v_lshl_add_u64 v[248:249], s[36:37], 0, v[128:129]
	s_mov_b32 m0, vcc_lo
	s_nop 0
	v_lshl_add_u64 v[248:249], s[26:27], 0, v[168:169]
	s_mov_b32 m0, s94
	s_nop 0
	s_mov_b32 m0, vcc_hi
	s_nop 0
	s_waitcnt vmcnt(2)
	s_waitcnt lgkmcnt(0)
	s_barrier
	s_setprio 1
	s_waitcnt lgkmcnt(0)
	v_mfma_f32_16x16x32_bf16 v[68:71], v[154:157], v[214:217], v[68:71]
	v_mfma_f32_16x16x32_bf16 v[64:67], v[162:165], v[214:217], v[64:67]
	v_mfma_f32_16x16x32_bf16 v[60:63], v[154:157], v[222:225], v[60:63]
	v_mfma_f32_16x16x32_bf16 v[56:59], v[162:165], v[222:225], v[56:59]
	v_mfma_f32_16x16x32_bf16 v[48:51], v[154:157], v[230:233], v[48:51]
	v_mfma_f32_16x16x32_bf16 v[40:43], v[162:165], v[230:233], v[40:43]
	v_mfma_f32_16x16x32_bf16 v[36:39], v[154:157], v[238:241], v[36:39]
	v_mfma_f32_16x16x32_bf16 v[32:35], v[162:165], v[238:241], v[32:35]
	v_mfma_f32_16x16x32_bf16 v[68:71], v[158:161], v[218:221], v[68:71]
	v_mfma_f32_16x16x32_bf16 v[64:67], v[194:197], v[218:221], v[64:67]
	v_mfma_f32_16x16x32_bf16 v[60:63], v[158:161], v[226:229], v[60:63]
	v_mfma_f32_16x16x32_bf16 v[56:59], v[194:197], v[226:229], v[56:59]
	v_mfma_f32_16x16x32_bf16 v[48:51], v[158:161], v[234:237], v[48:51]
	v_mfma_f32_16x16x32_bf16 v[40:43], v[194:197], v[234:237], v[40:43]
	v_mfma_f32_16x16x32_bf16 v[36:39], v[158:161], v[242:245], v[36:39]
	v_mfma_f32_16x16x32_bf16 v[32:35], v[194:197], v[242:245], v[32:35]
	s_setprio 0
	s_setprio 1
	v_mfma_f32_16x16x32_bf16 v[28:31], v[198:201], v[214:217], v[28:31]
	v_mfma_f32_16x16x32_bf16 v[24:27], v[206:209], v[214:217], v[24:27]
	v_mfma_f32_16x16x32_bf16 v[20:23], v[198:201], v[222:225], v[20:23]
	v_mfma_f32_16x16x32_bf16 v[16:19], v[206:209], v[222:225], v[16:19]
	v_mfma_f32_16x16x32_bf16 v[12:15], v[198:201], v[230:233], v[12:15]
	v_mfma_f32_16x16x32_bf16 v[8:11], v[206:209], v[230:233], v[8:11]
	v_mfma_f32_16x16x32_bf16 v[4:7], v[198:201], v[238:241], v[4:7]
	v_mfma_f32_16x16x32_bf16 v[0:3], v[206:209], v[238:241], v[0:3]
	v_mfma_f32_16x16x32_bf16 v[28:31], v[202:205], v[218:221], v[28:31]
	v_mfma_f32_16x16x32_bf16 v[24:27], v[210:213], v[218:221], v[24:27]
	v_mfma_f32_16x16x32_bf16 v[20:23], v[202:205], v[226:229], v[20:23]
	v_mfma_f32_16x16x32_bf16 v[16:19], v[210:213], v[226:229], v[16:19]
	v_mfma_f32_16x16x32_bf16 v[12:15], v[202:205], v[234:237], v[12:15]
	v_mfma_f32_16x16x32_bf16 v[8:11], v[210:213], v[234:237], v[8:11]
	v_mfma_f32_16x16x32_bf16 v[4:7], v[202:205], v[242:245], v[4:7]
	v_mfma_f32_16x16x32_bf16 v[0:3], v[210:213], v[242:245], v[0:3]
	s_setprio 0
	s_barrier
	ds_read_b128 v[154:157], v146
	ds_read_b128 v[158:161], v147
	ds_read_b128 v[162:165], v148
	ds_read_b128 v[194:197], v149
	ds_read_b128 v[198:201], v150
	ds_read_b128 v[202:205], v151
	ds_read_b128 v[206:209], v152
	ds_read_b128 v[210:213], v153
	s_add_u32 s26, s26, 0x40000
	s_addc_u32 s27, s27, 0
	s_mov_b32 m0, s28
	v_lshl_add_u64 v[180:181], s[26:27], 0, v[168:169]
	ds_read_b128 v[214:217], v137 offset:32768
	ds_read_b128 v[218:221], v137 offset:33792
	ds_read_b128 v[222:225], v137 offset:34816
	ds_read_b128 v[226:229], v137 offset:35840
	ds_read_b128 v[230:233], v137 offset:36864
	ds_read_b128 v[234:237], v137 offset:37888
	ds_read_b128 v[238:241], v137 offset:38912
	ds_read_b128 v[242:245], v137 offset:39936
	v_lshl_add_u64 v[180:181], s[26:27], 0, v[128:129]
	s_mov_b32 m0, s29
	s_nop 0
	s_waitcnt vmcnt(0)
	s_waitcnt lgkmcnt(0)
	s_barrier
	s_setprio 1
	s_waitcnt lgkmcnt(0)
	v_mfma_f32_16x16x32_bf16 v[124:127], v[154:157], v[214:217], v[124:127]
	v_mfma_f32_16x16x32_bf16 v[120:123], v[162:165], v[214:217], v[120:123]
	v_mfma_f32_16x16x32_bf16 v[116:119], v[154:157], v[222:225], v[116:119]
	v_mfma_f32_16x16x32_bf16 v[112:115], v[162:165], v[222:225], v[112:115]
	v_mfma_f32_16x16x32_bf16 v[108:111], v[154:157], v[230:233], v[108:111]
	v_mfma_f32_16x16x32_bf16 v[104:107], v[162:165], v[230:233], v[104:107]
	v_mfma_f32_16x16x32_bf16 v[76:79], v[154:157], v[238:241], v[76:79]
	v_mfma_f32_16x16x32_bf16 v[72:75], v[162:165], v[238:241], v[72:75]
	v_mfma_f32_16x16x32_bf16 v[124:127], v[158:161], v[218:221], v[124:127]
	v_mfma_f32_16x16x32_bf16 v[120:123], v[194:197], v[218:221], v[120:123]
	v_mfma_f32_16x16x32_bf16 v[116:119], v[158:161], v[226:229], v[116:119]
	v_mfma_f32_16x16x32_bf16 v[112:115], v[194:197], v[226:229], v[112:115]
	v_mfma_f32_16x16x32_bf16 v[108:111], v[158:161], v[234:237], v[108:111]
	v_mfma_f32_16x16x32_bf16 v[104:107], v[194:197], v[234:237], v[104:107]
	v_mfma_f32_16x16x32_bf16 v[76:79], v[158:161], v[242:245], v[76:79]
	v_mfma_f32_16x16x32_bf16 v[72:75], v[194:197], v[242:245], v[72:75]
	s_setprio 0
	s_setprio 1
	v_mfma_f32_16x16x32_bf16 v[100:103], v[198:201], v[214:217], v[100:103]
	v_mfma_f32_16x16x32_bf16 v[96:99], v[206:209], v[214:217], v[96:99]
	v_mfma_f32_16x16x32_bf16 v[92:95], v[198:201], v[222:225], v[92:95]
	v_mfma_f32_16x16x32_bf16 v[88:91], v[206:209], v[222:225], v[88:91]
	v_mfma_f32_16x16x32_bf16 v[84:87], v[198:201], v[230:233], v[84:87]
	v_mfma_f32_16x16x32_bf16 v[80:83], v[206:209], v[230:233], v[80:83]
	v_mfma_f32_16x16x32_bf16 v[52:55], v[198:201], v[238:241], v[52:55]
	v_mfma_f32_16x16x32_bf16 v[44:47], v[206:209], v[238:241], v[44:47]
	v_mfma_f32_16x16x32_bf16 v[100:103], v[202:205], v[218:221], v[100:103]
	v_mfma_f32_16x16x32_bf16 v[96:99], v[210:213], v[218:221], v[96:99]
	v_mfma_f32_16x16x32_bf16 v[92:95], v[202:205], v[226:229], v[92:95]
	v_mfma_f32_16x16x32_bf16 v[88:91], v[210:213], v[226:229], v[88:91]
	v_mfma_f32_16x16x32_bf16 v[84:87], v[202:205], v[234:237], v[84:87]
	v_mfma_f32_16x16x32_bf16 v[80:83], v[210:213], v[234:237], v[80:83]
	v_mfma_f32_16x16x32_bf16 v[52:55], v[202:205], v[242:245], v[52:55]
	v_mfma_f32_16x16x32_bf16 v[44:47], v[210:213], v[242:245], v[44:47]
	s_setprio 0
	s_barrier
	s_mov_b32 m0, s19
	v_lshl_add_u64 v[166:167], v[166:167], 0, s[34:35]
	s_add_u32 s14, s14, 0x40080
	ds_read_b128 v[214:217], v137 offset:49152
	ds_read_b128 v[218:221], v137 offset:50176
	ds_read_b128 v[222:225], v137 offset:51200
	ds_read_b128 v[226:229], v137 offset:52224
	ds_read_b128 v[230:233], v137 offset:53248
	ds_read_b128 v[234:237], v137 offset:54272
	ds_read_b128 v[238:241], v137 offset:55296
	ds_read_b128 v[242:245], v137 offset:56320
	v_lshl_add_u64 v[166:167], v[246:247], 0, s[34:35]
	s_mov_b32 m0, s30
	s_addc_u32 s15, s15, 0
	v_lshl_add_u64 v[166:167], s[14:15], 0, v[168:169]
	s_mov_b32 m0, s63
	s_nop 0
	v_lshl_add_u64 v[166:167], s[14:15], 0, v[128:129]
	s_mov_b32 m0, s24
	s_nop 0
	v_lshl_add_u64 v[166:167], v[248:249], 0, s[34:35]
	s_mov_b32 m0, s61
	s_nop 0
	v_lshl_add_u64 v[166:167], v[250:251], 0, s[34:35]
	s_mov_b32 m0, s62
	s_nop 0
	s_waitcnt vmcnt(0)
	s_waitcnt lgkmcnt(0)
	s_barrier
	s_setprio 1
	s_waitcnt lgkmcnt(0)
	v_mfma_f32_16x16x32_bf16 v[68:71], v[154:157], v[214:217], v[68:71]
	v_mfma_f32_16x16x32_bf16 v[64:67], v[162:165], v[214:217], v[64:67]
	v_mfma_f32_16x16x32_bf16 v[60:63], v[154:157], v[222:225], v[60:63]
	v_mfma_f32_16x16x32_bf16 v[56:59], v[162:165], v[222:225], v[56:59]
	v_mfma_f32_16x16x32_bf16 v[48:51], v[154:157], v[230:233], v[48:51]
	v_mfma_f32_16x16x32_bf16 v[40:43], v[162:165], v[230:233], v[40:43]
	v_mfma_f32_16x16x32_bf16 v[36:39], v[154:157], v[238:241], v[36:39]
	v_mfma_f32_16x16x32_bf16 v[32:35], v[162:165], v[238:241], v[32:35]
	v_mfma_f32_16x16x32_bf16 v[68:71], v[158:161], v[218:221], v[68:71]
	v_mfma_f32_16x16x32_bf16 v[64:67], v[194:197], v[218:221], v[64:67]
	v_mfma_f32_16x16x32_bf16 v[60:63], v[158:161], v[226:229], v[60:63]
	v_mfma_f32_16x16x32_bf16 v[56:59], v[194:197], v[226:229], v[56:59]
	v_mfma_f32_16x16x32_bf16 v[48:51], v[158:161], v[234:237], v[48:51]
	v_mfma_f32_16x16x32_bf16 v[40:43], v[194:197], v[234:237], v[40:43]
	v_mfma_f32_16x16x32_bf16 v[36:39], v[158:161], v[242:245], v[36:39]
	v_mfma_f32_16x16x32_bf16 v[32:35], v[194:197], v[242:245], v[32:35]
	s_setprio 0
	s_setprio 1
	v_mfma_f32_16x16x32_bf16 v[28:31], v[198:201], v[214:217], v[28:31]
	v_mfma_f32_16x16x32_bf16 v[24:27], v[206:209], v[214:217], v[24:27]
	v_mfma_f32_16x16x32_bf16 v[20:23], v[198:201], v[222:225], v[20:23]
	v_mfma_f32_16x16x32_bf16 v[16:19], v[206:209], v[222:225], v[16:19]
	v_mfma_f32_16x16x32_bf16 v[12:15], v[198:201], v[230:233], v[12:15]
	v_mfma_f32_16x16x32_bf16 v[8:11], v[206:209], v[230:233], v[8:11]
	v_mfma_f32_16x16x32_bf16 v[4:7], v[198:201], v[238:241], v[4:7]
	v_mfma_f32_16x16x32_bf16 v[0:3], v[206:209], v[238:241], v[0:3]
	v_mfma_f32_16x16x32_bf16 v[28:31], v[202:205], v[218:221], v[28:31]
	v_mfma_f32_16x16x32_bf16 v[24:27], v[210:213], v[218:221], v[24:27]
	v_mfma_f32_16x16x32_bf16 v[20:23], v[202:205], v[226:229], v[20:23]
	v_mfma_f32_16x16x32_bf16 v[16:19], v[210:213], v[226:229], v[16:19]
	v_mfma_f32_16x16x32_bf16 v[12:15], v[202:205], v[234:237], v[12:15]
	v_mfma_f32_16x16x32_bf16 v[8:11], v[210:213], v[234:237], v[8:11]
	v_mfma_f32_16x16x32_bf16 v[4:7], v[202:205], v[242:245], v[4:7]
	v_mfma_f32_16x16x32_bf16 v[0:3], v[210:213], v[242:245], v[0:3]
	s_setprio 0
	s_barrier
	s_add_i32 s60, s60, 2
	s_add_u32 s88, s88, 0x100
	s_addc_u32 s89, s89, 0
	s_cmp_lt_u32 s60, 14
	v_lshrrev_b32_e32 v248, 1, v192
	v_and_b32_e32 v249, 1, v192
	v_lshlrev_b32_e32 v248, 11, v248
	v_lshl_or_b32 v248, v249, 7, v248
	v_add_u32_e32 v248, 0x3f8000, v248
	v_mov_b32_e32 v249, 0
	v_lshl_add_u64 v[248:249], s[86:87], 0, v[248:249]
	s_waitcnt vmcnt(0)
	s_cmpk_gt_u32 s92, 0xff
	s_cbranch_scc1 .LBB0_27
	s_barrier

.LBB0_76:
	s_add_i32 s36, s14, 2
	s_add_u32 s48, s26, 0x100
	s_addc_u32 s49, s27, 0
	v_or_b32_e32 v138, 0x10000, v136
	v_add_u32_e32 v142, 0x10400, v136
	v_add_u32_e32 v146, 0x10800, v136
	v_add_u32_e32 v150, 0x10c00, v136
	v_or_b32_e32 v154, 0x14000, v136
	v_add_u32_e32 v158, 0x14400, v136
	v_add_u32_e32 v162, 0x14800, v136
	s_cmp_lg_u32 s63, s14
	ds_read_b128 v[138:141], v138
	ds_read_b128 v[142:145], v142
	ds_read_b128 v[146:149], v146
	ds_read_b128 v[150:153], v150
	ds_read_b128 v[154:157], v154
	ds_read_b128 v[158:161], v158
	v_add_u32_e32 v166, 0x14c00, v136
	ds_read_b128 v[162:165], v162
	ds_read_b128 v[194:197], v166
	s_cselect_b32 s44, s48, 0
	s_cselect_b32 s37, s49, 0
	s_add_u32 s14, s42, s44
	s_addc_u32 s15, s43, s37
	s_add_u32 s44, s40, s44
	s_addc_u32 s45, s41, s37
	v_lshl_add_u64 v[166:167], v[130:131], 0, s[26:27]
	s_add_i32 m0, s90, 0xc000
	ds_read_b128 v[198:201], v137
	ds_read_b128 v[202:205], v137 offset:1024
	ds_read_b128 v[206:209], v137 offset:2048
	ds_read_b128 v[210:213], v137 offset:3072
	ds_read_b128 v[214:217], v137 offset:4096
	ds_read_b128 v[218:221], v137 offset:5120
	ds_read_b128 v[222:225], v137 offset:6144
	ds_read_b128 v[226:229], v137 offset:7168
	global_load_lds_dwordx4 v[166:167], off
	v_lshl_add_u64 v[166:167], v[132:133], 0, s[26:27]
	s_add_i32 m0, s90, 0xe000
	s_nop 0
	global_load_lds_dwordx4 v[166:167], off
	s_waitcnt vmcnt(8)
	s_waitcnt lgkmcnt(0)
	s_barrier
	s_setprio 1
	s_waitcnt lgkmcnt(0)
	v_mfma_f32_16x16x32_bf16 v[124:127], v[138:141], v[198:201], v[124:127]
	v_mfma_f32_16x16x32_bf16 v[120:123], v[146:149], v[198:201], v[120:123]
	v_mfma_f32_16x16x32_bf16 v[116:119], v[138:141], v[206:209], v[116:119]
	v_mfma_f32_16x16x32_bf16 v[112:115], v[146:149], v[206:209], v[112:115]
	v_mfma_f32_16x16x32_bf16 v[108:111], v[138:141], v[214:217], v[108:111]
	v_mfma_f32_16x16x32_bf16 v[104:107], v[146:149], v[214:217], v[104:107]
	v_mfma_f32_16x16x32_bf16 v[100:103], v[138:141], v[222:225], v[100:103]
	v_mfma_f32_16x16x32_bf16 v[96:99], v[146:149], v[222:225], v[96:99]
	v_mfma_f32_16x16x32_bf16 v[124:127], v[142:145], v[202:205], v[124:127]
	v_mfma_f32_16x16x32_bf16 v[120:123], v[150:153], v[202:205], v[120:123]
	v_mfma_f32_16x16x32_bf16 v[116:119], v[142:145], v[210:213], v[116:119]
	v_mfma_f32_16x16x32_bf16 v[112:115], v[150:153], v[210:213], v[112:115]
	v_mfma_f32_16x16x32_bf16 v[108:111], v[142:145], v[218:221], v[108:111]
	v_mfma_f32_16x16x32_bf16 v[104:107], v[150:153], v[218:221], v[104:107]
	v_mfma_f32_16x16x32_bf16 v[100:103], v[142:145], v[226:229], v[100:103]
	v_mfma_f32_16x16x32_bf16 v[96:99], v[150:153], v[226:229], v[96:99]
	s_setprio 0
	s_setprio 1
	v_mfma_f32_16x16x32_bf16 v[92:95], v[154:157], v[198:201], v[92:95]
	v_mfma_f32_16x16x32_bf16 v[88:91], v[162:165], v[198:201], v[88:91]
	v_mfma_f32_16x16x32_bf16 v[84:87], v[154:157], v[206:209], v[84:87]
	v_mfma_f32_16x16x32_bf16 v[80:83], v[162:165], v[206:209], v[80:83]
	v_mfma_f32_16x16x32_bf16 v[76:79], v[154:157], v[214:217], v[76:79]
	v_mfma_f32_16x16x32_bf16 v[72:75], v[162:165], v[214:217], v[72:75]
	v_mfma_f32_16x16x32_bf16 v[68:71], v[154:157], v[222:225], v[68:71]
	v_mfma_f32_16x16x32_bf16 v[64:67], v[162:165], v[222:225], v[64:67]
	v_mfma_f32_16x16x32_bf16 v[92:95], v[158:161], v[202:205], v[92:95]
	v_mfma_f32_16x16x32_bf16 v[88:91], v[194:197], v[202:205], v[88:91]
	v_mfma_f32_16x16x32_bf16 v[84:87], v[158:161], v[210:213], v[84:87]
	v_mfma_f32_16x16x32_bf16 v[80:83], v[194:197], v[210:213], v[80:83]
	v_mfma_f32_16x16x32_bf16 v[76:79], v[158:161], v[218:221], v[76:79]
	v_mfma_f32_16x16x32_bf16 v[72:75], v[194:197], v[218:221], v[72:75]
	v_mfma_f32_16x16x32_bf16 v[68:71], v[158:161], v[226:229], v[68:71]
	v_mfma_f32_16x16x32_bf16 v[64:67], v[194:197], v[226:229], v[64:67]
	s_setprio 0
	s_barrier
	s_mov_b32 m0, s28
	v_lshl_add_u64 v[166:167], s[44:45], 0, v[168:169]
	s_add_u32 s26, s44, s56
	ds_read_b128 v[198:201], v137 offset:16384
	ds_read_b128 v[202:205], v137 offset:17408
	ds_read_b128 v[206:209], v137 offset:18432
	ds_read_b128 v[210:213], v137 offset:19456
	ds_read_b128 v[214:217], v137 offset:20480
	ds_read_b128 v[218:221], v137 offset:21504
	ds_read_b128 v[222:225], v137 offset:22528
	ds_read_b128 v[226:229], v137 offset:23552
	global_load_lds_dwordx4 v[166:167], off
	v_lshl_add_u64 v[230:231], s[44:45], 0, v[128:129]
	s_mov_b32 m0, s29
	s_addc_u32 s27, s45, 0
	global_load_lds_dwordx4 v[230:231], off
	v_lshl_add_u64 v[232:233], s[26:27], 0, v[168:169]
	s_mov_b32 m0, s91
	v_lshl_add_u64 v[234:235], s[26:27], 0, v[128:129]
	global_load_lds_dwordx4 v[232:233], off
	s_mov_b32 m0, s92
	v_lshl_add_u64 v[236:237], s[14:15], 0, v[168:169]
	global_load_lds_dwordx4 v[234:235], off
	s_mov_b32 m0, s90
	v_lshl_add_u64 v[238:239], s[14:15], 0, v[128:129]
	global_load_lds_dwordx4 v[236:237], off
	s_mov_b32 m0, s93
	s_nop 0
	global_load_lds_dwordx4 v[238:239], off
	s_waitcnt vmcnt(8)
	s_waitcnt lgkmcnt(0)
	s_barrier
	s_setprio 1
	s_waitcnt lgkmcnt(0)
	v_mfma_f32_16x16x32_bf16 v[60:63], v[138:141], v[198:201], v[60:63]
	v_mfma_f32_16x16x32_bf16 v[56:59], v[146:149], v[198:201], v[56:59]
	v_mfma_f32_16x16x32_bf16 v[52:55], v[138:141], v[206:209], v[52:55]
	v_mfma_f32_16x16x32_bf16 v[48:51], v[146:149], v[206:209], v[48:51]
	v_mfma_f32_16x16x32_bf16 v[44:47], v[138:141], v[214:217], v[44:47]
	v_mfma_f32_16x16x32_bf16 v[40:43], v[146:149], v[214:217], v[40:43]
	v_mfma_f32_16x16x32_bf16 v[36:39], v[138:141], v[222:225], v[36:39]
	v_mfma_f32_16x16x32_bf16 v[32:35], v[146:149], v[222:225], v[32:35]
	v_mfma_f32_16x16x32_bf16 v[60:63], v[142:145], v[202:205], v[60:63]
	v_mfma_f32_16x16x32_bf16 v[56:59], v[150:153], v[202:205], v[56:59]
	v_mfma_f32_16x16x32_bf16 v[52:55], v[142:145], v[210:213], v[52:55]
	v_mfma_f32_16x16x32_bf16 v[48:51], v[150:153], v[210:213], v[48:51]
	v_mfma_f32_16x16x32_bf16 v[44:47], v[142:145], v[218:221], v[44:47]
	v_mfma_f32_16x16x32_bf16 v[40:43], v[150:153], v[218:221], v[40:43]
	v_mfma_f32_16x16x32_bf16 v[36:39], v[142:145], v[226:229], v[36:39]
	v_mfma_f32_16x16x32_bf16 v[32:35], v[150:153], v[226:229], v[32:35]
	s_setprio 0
	s_setprio 1
	v_mfma_f32_16x16x32_bf16 v[28:31], v[154:157], v[198:201], v[28:31]
	v_mfma_f32_16x16x32_bf16 v[24:27], v[162:165], v[198:201], v[24:27]
	v_mfma_f32_16x16x32_bf16 v[20:23], v[154:157], v[206:209], v[20:23]
	v_mfma_f32_16x16x32_bf16 v[16:19], v[162:165], v[206:209], v[16:19]
	v_mfma_f32_16x16x32_bf16 v[12:15], v[154:157], v[214:217], v[12:15]
	v_mfma_f32_16x16x32_bf16 v[8:11], v[162:165], v[214:217], v[8:11]
	v_mfma_f32_16x16x32_bf16 v[4:7], v[154:157], v[222:225], v[4:7]
	v_mfma_f32_16x16x32_bf16 v[0:3], v[162:165], v[222:225], v[0:3]
	v_mfma_f32_16x16x32_bf16 v[28:31], v[158:161], v[202:205], v[28:31]
	v_mfma_f32_16x16x32_bf16 v[24:27], v[194:197], v[202:205], v[24:27]
	v_mfma_f32_16x16x32_bf16 v[20:23], v[158:161], v[210:213], v[20:23]
	v_mfma_f32_16x16x32_bf16 v[16:19], v[194:197], v[210:213], v[16:19]
	v_mfma_f32_16x16x32_bf16 v[12:15], v[158:161], v[218:221], v[12:15]
	v_mfma_f32_16x16x32_bf16 v[8:11], v[194:197], v[218:221], v[8:11]
	v_mfma_f32_16x16x32_bf16 v[4:7], v[158:161], v[226:229], v[4:7]
	v_mfma_f32_16x16x32_bf16 v[0:3], v[194:197], v[226:229], v[0:3]
	s_setprio 0
	s_barrier
	v_or_b32_e32 v138, 0x18000, v136
	v_add_u32_e32 v142, 0x18400, v136
	v_add_u32_e32 v146, 0x18800, v136
	v_add_u32_e32 v150, 0x18c00, v136
	v_or_b32_e32 v154, 0x1c000, v136
	v_add_u32_e32 v158, 0x1c400, v136
	v_add_u32_e32 v162, 0x1c800, v136
	ds_read_b128 v[138:141], v138
	ds_read_b128 v[142:145], v142
	ds_read_b128 v[146:149], v146
	ds_read_b128 v[150:153], v150
	ds_read_b128 v[154:157], v154
	ds_read_b128 v[158:161], v158
	v_add_u32_e32 v180, 0x1cc00, v136
	ds_read_b128 v[162:165], v162
	ds_read_b128 v[194:197], v180
	s_add_u32 s14, s14, s56
	s_addc_u32 s15, s15, 0
	s_mov_b32 m0, s94
	v_lshl_add_u64 v[240:241], s[14:15], 0, v[168:169]
	ds_read_b128 v[198:201], v137 offset:32768
	ds_read_b128 v[202:205], v137 offset:33792
	ds_read_b128 v[206:209], v137 offset:34816
	ds_read_b128 v[210:213], v137 offset:35840
	ds_read_b128 v[214:217], v137 offset:36864
	ds_read_b128 v[218:221], v137 offset:37888
	ds_read_b128 v[222:225], v137 offset:38912
	ds_read_b128 v[226:229], v137 offset:39936
	global_load_lds_dwordx4 v[240:241], off
	v_lshl_add_u64 v[240:241], s[14:15], 0, v[128:129]
	s_mov_b32 m0, vcc_lo
	s_nop 0
	global_load_lds_dwordx4 v[240:241], off
	s_waitcnt vmcnt(8)
	s_waitcnt lgkmcnt(0)
	s_barrier
	s_setprio 1
	s_waitcnt lgkmcnt(0)
	v_mfma_f32_16x16x32_bf16 v[124:127], v[138:141], v[198:201], v[124:127]
	v_mfma_f32_16x16x32_bf16 v[120:123], v[146:149], v[198:201], v[120:123]
	v_mfma_f32_16x16x32_bf16 v[116:119], v[138:141], v[206:209], v[116:119]
	v_mfma_f32_16x16x32_bf16 v[112:115], v[146:149], v[206:209], v[112:115]
	v_mfma_f32_16x16x32_bf16 v[108:111], v[138:141], v[214:217], v[108:111]
	v_mfma_f32_16x16x32_bf16 v[104:107], v[146:149], v[214:217], v[104:107]
	v_mfma_f32_16x16x32_bf16 v[100:103], v[138:141], v[222:225], v[100:103]
	v_mfma_f32_16x16x32_bf16 v[96:99], v[146:149], v[222:225], v[96:99]
	v_mfma_f32_16x16x32_bf16 v[124:127], v[142:145], v[202:205], v[124:127]
	v_mfma_f32_16x16x32_bf16 v[120:123], v[150:153], v[202:205], v[120:123]
	v_mfma_f32_16x16x32_bf16 v[116:119], v[142:145], v[210:213], v[116:119]
	v_mfma_f32_16x16x32_bf16 v[112:115], v[150:153], v[210:213], v[112:115]
	v_mfma_f32_16x16x32_bf16 v[108:111], v[142:145], v[218:221], v[108:111]
	v_mfma_f32_16x16x32_bf16 v[104:107], v[150:153], v[218:221], v[104:107]
	v_mfma_f32_16x16x32_bf16 v[100:103], v[142:145], v[226:229], v[100:103]
	v_mfma_f32_16x16x32_bf16 v[96:99], v[150:153], v[226:229], v[96:99]
	s_setprio 0
	s_setprio 1
	v_mfma_f32_16x16x32_bf16 v[92:95], v[154:157], v[198:201], v[92:95]
	v_mfma_f32_16x16x32_bf16 v[88:91], v[162:165], v[198:201], v[88:91]
	v_mfma_f32_16x16x32_bf16 v[84:87], v[154:157], v[206:209], v[84:87]
	v_mfma_f32_16x16x32_bf16 v[80:83], v[162:165], v[206:209], v[80:83]
	v_mfma_f32_16x16x32_bf16 v[76:79], v[154:157], v[214:217], v[76:79]
	v_mfma_f32_16x16x32_bf16 v[72:75], v[162:165], v[214:217], v[72:75]
	v_mfma_f32_16x16x32_bf16 v[68:71], v[154:157], v[222:225], v[68:71]
	v_mfma_f32_16x16x32_bf16 v[64:67], v[162:165], v[222:225], v[64:67]
	v_mfma_f32_16x16x32_bf16 v[92:95], v[158:161], v[202:205], v[92:95]
	v_mfma_f32_16x16x32_bf16 v[88:91], v[194:197], v[202:205], v[88:91]
	v_mfma_f32_16x16x32_bf16 v[84:87], v[158:161], v[210:213], v[84:87]
	v_mfma_f32_16x16x32_bf16 v[80:83], v[194:197], v[210:213], v[80:83]
	v_mfma_f32_16x16x32_bf16 v[76:79], v[158:161], v[218:221], v[76:79]
	v_mfma_f32_16x16x32_bf16 v[72:75], v[194:197], v[218:221], v[72:75]
	v_mfma_f32_16x16x32_bf16 v[68:71], v[158:161], v[226:229], v[68:71]
	v_mfma_f32_16x16x32_bf16 v[64:67], v[194:197], v[226:229], v[64:67]
	s_setprio 0
	s_barrier
	s_mov_b32 m0, s17
	v_lshl_add_u64 v[166:167], v[166:167], 0, s[34:35]
	ds_read_b128 v[198:201], v137 offset:49152
	ds_read_b128 v[202:205], v137 offset:50176
	ds_read_b128 v[206:209], v137 offset:51200
	ds_read_b128 v[210:213], v137 offset:52224
	ds_read_b128 v[214:217], v137 offset:53248
	ds_read_b128 v[218:221], v137 offset:54272
	ds_read_b128 v[222:225], v137 offset:55296
	ds_read_b128 v[226:229], v137 offset:56320
	global_load_lds_dwordx4 v[166:167], off
	v_lshl_add_u64 v[166:167], v[230:231], 0, s[34:35]
	s_mov_b32 m0, s24
	s_nop 0
	global_load_lds_dwordx4 v[166:167], off
	v_lshl_add_u64 v[166:167], v[232:233], 0, s[34:35]
	s_mov_b32 m0, s97
	s_nop 0
	global_load_lds_dwordx4 v[166:167], off
	v_lshl_add_u64 v[166:167], v[234:235], 0, s[34:35]
	s_mov_b32 m0, vcc_hi
	s_nop 0
	global_load_lds_dwordx4 v[166:167], off
	v_lshl_add_u64 v[166:167], v[236:237], 0, s[34:35]
	s_mov_b32 m0, s60
	s_nop 0
	global_load_lds_dwordx4 v[166:167], off
	v_lshl_add_u64 v[166:167], v[238:239], 0, s[34:35]
	s_mov_b32 m0, s96
	s_nop 0
	global_load_lds_dwordx4 v[166:167], off
	s_waitcnt vmcnt(8)
	s_waitcnt lgkmcnt(0)
	s_barrier
	s_setprio 1
	s_waitcnt lgkmcnt(0)
	v_mfma_f32_16x16x32_bf16 v[60:63], v[138:141], v[198:201], v[60:63]
	v_mfma_f32_16x16x32_bf16 v[56:59], v[146:149], v[198:201], v[56:59]
	v_mfma_f32_16x16x32_bf16 v[52:55], v[138:141], v[206:209], v[52:55]
	v_mfma_f32_16x16x32_bf16 v[48:51], v[146:149], v[206:209], v[48:51]
	v_mfma_f32_16x16x32_bf16 v[44:47], v[138:141], v[214:217], v[44:47]
	v_mfma_f32_16x16x32_bf16 v[40:43], v[146:149], v[214:217], v[40:43]
	v_mfma_f32_16x16x32_bf16 v[36:39], v[138:141], v[222:225], v[36:39]
	v_mfma_f32_16x16x32_bf16 v[32:35], v[146:149], v[222:225], v[32:35]
	v_mfma_f32_16x16x32_bf16 v[60:63], v[142:145], v[202:205], v[60:63]
	v_mfma_f32_16x16x32_bf16 v[56:59], v[150:153], v[202:205], v[56:59]
	v_mfma_f32_16x16x32_bf16 v[52:55], v[142:145], v[210:213], v[52:55]
	v_mfma_f32_16x16x32_bf16 v[48:51], v[150:153], v[210:213], v[48:51]
	v_mfma_f32_16x16x32_bf16 v[44:47], v[142:145], v[218:221], v[44:47]
	v_mfma_f32_16x16x32_bf16 v[40:43], v[150:153], v[218:221], v[40:43]
	v_mfma_f32_16x16x32_bf16 v[36:39], v[142:145], v[226:229], v[36:39]
	v_mfma_f32_16x16x32_bf16 v[32:35], v[150:153], v[226:229], v[32:35]
	s_setprio 0
	s_setprio 1
	v_mfma_f32_16x16x32_bf16 v[28:31], v[154:157], v[198:201], v[28:31]
	v_mfma_f32_16x16x32_bf16 v[24:27], v[162:165], v[198:201], v[24:27]
	v_mfma_f32_16x16x32_bf16 v[20:23], v[154:157], v[206:209], v[20:23]
	v_mfma_f32_16x16x32_bf16 v[16:19], v[162:165], v[206:209], v[16:19]
	v_mfma_f32_16x16x32_bf16 v[12:15], v[154:157], v[214:217], v[12:15]
	v_mfma_f32_16x16x32_bf16 v[8:11], v[162:165], v[214:217], v[8:11]
	v_mfma_f32_16x16x32_bf16 v[4:7], v[154:157], v[222:225], v[4:7]
	v_mfma_f32_16x16x32_bf16 v[0:3], v[162:165], v[222:225], v[0:3]
	v_mfma_f32_16x16x32_bf16 v[28:31], v[158:161], v[202:205], v[28:31]
	v_mfma_f32_16x16x32_bf16 v[24:27], v[194:197], v[202:205], v[24:27]
	v_mfma_f32_16x16x32_bf16 v[20:23], v[158:161], v[210:213], v[20:23]
	v_mfma_f32_16x16x32_bf16 v[16:19], v[194:197], v[210:213], v[16:19]
	v_mfma_f32_16x16x32_bf16 v[12:15], v[158:161], v[218:221], v[12:15]
	v_mfma_f32_16x16x32_bf16 v[8:11], v[194:197], v[218:221], v[8:11]
	v_mfma_f32_16x16x32_bf16 v[4:7], v[158:161], v[226:229], v[4:7]
	v_mfma_f32_16x16x32_bf16 v[0:3], v[194:197], v[226:229], v[0:3]
	s_setprio 0
	s_cmp_lt_u32 s36, s63
	s_mov_b64 s[26:27], s[48:49]
	s_mov_b32 s14, s36
	s_barrier
	s_cbranch_scc1 .LBB0_76
	s_add_i32 s36, s14, 2
	s_add_u32 s48, s26, 0x100
	s_addc_u32 s49, s27, 0
	v_or_b32_e32 v138, 0x10000, v136
	v_add_u32_e32 v142, 0x10400, v136
	v_add_u32_e32 v146, 0x10800, v136
	v_add_u32_e32 v150, 0x10c00, v136
	v_or_b32_e32 v154, 0x14000, v136
	v_add_u32_e32 v158, 0x14400, v136
	v_add_u32_e32 v162, 0x14800, v136
	s_cmp_lg_u32 s63, s14
	ds_read_b128 v[138:141], v138
	ds_read_b128 v[142:145], v142
	ds_read_b128 v[146:149], v146
	ds_read_b128 v[150:153], v150
	ds_read_b128 v[154:157], v154
	ds_read_b128 v[158:161], v158
	v_add_u32_e32 v166, 0x14c00, v136
	ds_read_b128 v[162:165], v162
	ds_read_b128 v[194:197], v166
	s_cselect_b32 s44, s48, 0
	s_cselect_b32 s37, s49, 0
	s_add_u32 s14, s42, s44
	s_addc_u32 s15, s43, s37
	s_add_u32 s44, s40, s44
	s_addc_u32 s45, s41, s37
	v_lshl_add_u64 v[166:167], v[130:131], 0, s[26:27]
	s_add_i32 m0, s90, 0xc000
	ds_read_b128 v[198:201], v137
	ds_read_b128 v[202:205], v137 offset:1024
	ds_read_b128 v[206:209], v137 offset:2048
	ds_read_b128 v[210:213], v137 offset:3072
	ds_read_b128 v[214:217], v137 offset:4096
	ds_read_b128 v[218:221], v137 offset:5120
	ds_read_b128 v[222:225], v137 offset:6144
	ds_read_b128 v[226:229], v137 offset:7168
	global_load_lds_dwordx4 v[166:167], off
	v_lshl_add_u64 v[166:167], v[132:133], 0, s[26:27]
	s_add_i32 m0, s90, 0xe000
	s_nop 0
	global_load_lds_dwordx4 v[166:167], off
	s_waitcnt vmcnt(8)
	s_waitcnt lgkmcnt(0)
	s_barrier
	s_setprio 1
	s_waitcnt lgkmcnt(0)
	v_mfma_f32_16x16x32_bf16 v[124:127], v[138:141], v[198:201], v[124:127]
	v_mfma_f32_16x16x32_bf16 v[120:123], v[146:149], v[198:201], v[120:123]
	v_mfma_f32_16x16x32_bf16 v[116:119], v[138:141], v[206:209], v[116:119]
	v_mfma_f32_16x16x32_bf16 v[112:115], v[146:149], v[206:209], v[112:115]
	v_mfma_f32_16x16x32_bf16 v[108:111], v[138:141], v[214:217], v[108:111]
	v_mfma_f32_16x16x32_bf16 v[104:107], v[146:149], v[214:217], v[104:107]
	v_mfma_f32_16x16x32_bf16 v[100:103], v[138:141], v[222:225], v[100:103]
	v_mfma_f32_16x16x32_bf16 v[96:99], v[146:149], v[222:225], v[96:99]
	v_mfma_f32_16x16x32_bf16 v[124:127], v[142:145], v[202:205], v[124:127]
	v_mfma_f32_16x16x32_bf16 v[120:123], v[150:153], v[202:205], v[120:123]
	v_mfma_f32_16x16x32_bf16 v[116:119], v[142:145], v[210:213], v[116:119]
	v_mfma_f32_16x16x32_bf16 v[112:115], v[150:153], v[210:213], v[112:115]
	v_mfma_f32_16x16x32_bf16 v[108:111], v[142:145], v[218:221], v[108:111]
	v_mfma_f32_16x16x32_bf16 v[104:107], v[150:153], v[218:221], v[104:107]
	v_mfma_f32_16x16x32_bf16 v[100:103], v[142:145], v[226:229], v[100:103]
	v_mfma_f32_16x16x32_bf16 v[96:99], v[150:153], v[226:229], v[96:99]
	s_setprio 0
	s_setprio 1
	v_mfma_f32_16x16x32_bf16 v[92:95], v[154:157], v[198:201], v[92:95]
	v_mfma_f32_16x16x32_bf16 v[88:91], v[162:165], v[198:201], v[88:91]
	v_mfma_f32_16x16x32_bf16 v[84:87], v[154:157], v[206:209], v[84:87]
	v_mfma_f32_16x16x32_bf16 v[80:83], v[162:165], v[206:209], v[80:83]
	v_mfma_f32_16x16x32_bf16 v[76:79], v[154:157], v[214:217], v[76:79]
	v_mfma_f32_16x16x32_bf16 v[72:75], v[162:165], v[214:217], v[72:75]
	v_mfma_f32_16x16x32_bf16 v[68:71], v[154:157], v[222:225], v[68:71]
	v_mfma_f32_16x16x32_bf16 v[64:67], v[162:165], v[222:225], v[64:67]
	v_mfma_f32_16x16x32_bf16 v[92:95], v[158:161], v[202:205], v[92:95]
	v_mfma_f32_16x16x32_bf16 v[88:91], v[194:197], v[202:205], v[88:91]
	v_mfma_f32_16x16x32_bf16 v[84:87], v[158:161], v[210:213], v[84:87]
	v_mfma_f32_16x16x32_bf16 v[80:83], v[194:197], v[210:213], v[80:83]
	v_mfma_f32_16x16x32_bf16 v[76:79], v[158:161], v[218:221], v[76:79]
	v_mfma_f32_16x16x32_bf16 v[72:75], v[194:197], v[218:221], v[72:75]
	v_mfma_f32_16x16x32_bf16 v[68:71], v[158:161], v[226:229], v[68:71]
	v_mfma_f32_16x16x32_bf16 v[64:67], v[194:197], v[226:229], v[64:67]
	s_setprio 0
	s_barrier
	s_mov_b32 m0, s28
	v_lshl_add_u64 v[166:167], s[44:45], 0, v[168:169]
	s_add_u32 s26, s44, s56
	ds_read_b128 v[198:201], v137 offset:16384
	ds_read_b128 v[202:205], v137 offset:17408
	ds_read_b128 v[206:209], v137 offset:18432
	ds_read_b128 v[210:213], v137 offset:19456
	ds_read_b128 v[214:217], v137 offset:20480
	ds_read_b128 v[218:221], v137 offset:21504
	ds_read_b128 v[222:225], v137 offset:22528
	ds_read_b128 v[226:229], v137 offset:23552
	v_lshl_add_u64 v[230:231], s[44:45], 0, v[128:129]
	s_mov_b32 m0, s29
	s_addc_u32 s27, s45, 0
	v_lshl_add_u64 v[232:233], s[26:27], 0, v[168:169]
	s_mov_b32 m0, s91
	v_lshl_add_u64 v[234:235], s[26:27], 0, v[128:129]
	s_mov_b32 m0, s92
	v_lshl_add_u64 v[236:237], s[14:15], 0, v[168:169]
	s_mov_b32 m0, s90
	v_lshl_add_u64 v[238:239], s[14:15], 0, v[128:129]
	s_mov_b32 m0, s93
	s_nop 0
	s_waitcnt vmcnt(2)
	s_waitcnt lgkmcnt(0)
	s_barrier
	s_setprio 1
	s_waitcnt lgkmcnt(0)
	v_mfma_f32_16x16x32_bf16 v[60:63], v[138:141], v[198:201], v[60:63]
	v_mfma_f32_16x16x32_bf16 v[56:59], v[146:149], v[198:201], v[56:59]
	v_mfma_f32_16x16x32_bf16 v[52:55], v[138:141], v[206:209], v[52:55]
	v_mfma_f32_16x16x32_bf16 v[48:51], v[146:149], v[206:209], v[48:51]
	v_mfma_f32_16x16x32_bf16 v[44:47], v[138:141], v[214:217], v[44:47]
	v_mfma_f32_16x16x32_bf16 v[40:43], v[146:149], v[214:217], v[40:43]
	v_mfma_f32_16x16x32_bf16 v[36:39], v[138:141], v[222:225], v[36:39]
	v_mfma_f32_16x16x32_bf16 v[32:35], v[146:149], v[222:225], v[32:35]
	v_mfma_f32_16x16x32_bf16 v[60:63], v[142:145], v[202:205], v[60:63]
	v_mfma_f32_16x16x32_bf16 v[56:59], v[150:153], v[202:205], v[56:59]
	v_mfma_f32_16x16x32_bf16 v[52:55], v[142:145], v[210:213], v[52:55]
	v_mfma_f32_16x16x32_bf16 v[48:51], v[150:153], v[210:213], v[48:51]
	v_mfma_f32_16x16x32_bf16 v[44:47], v[142:145], v[218:221], v[44:47]
	v_mfma_f32_16x16x32_bf16 v[40:43], v[150:153], v[218:221], v[40:43]
	v_mfma_f32_16x16x32_bf16 v[36:39], v[142:145], v[226:229], v[36:39]
	v_mfma_f32_16x16x32_bf16 v[32:35], v[150:153], v[226:229], v[32:35]
	s_setprio 0
	s_setprio 1
	v_mfma_f32_16x16x32_bf16 v[28:31], v[154:157], v[198:201], v[28:31]
	v_mfma_f32_16x16x32_bf16 v[24:27], v[162:165], v[198:201], v[24:27]
	v_mfma_f32_16x16x32_bf16 v[20:23], v[154:157], v[206:209], v[20:23]
	v_mfma_f32_16x16x32_bf16 v[16:19], v[162:165], v[206:209], v[16:19]
	v_mfma_f32_16x16x32_bf16 v[12:15], v[154:157], v[214:217], v[12:15]
	v_mfma_f32_16x16x32_bf16 v[8:11], v[162:165], v[214:217], v[8:11]
	v_mfma_f32_16x16x32_bf16 v[4:7], v[154:157], v[222:225], v[4:7]
	v_mfma_f32_16x16x32_bf16 v[0:3], v[162:165], v[222:225], v[0:3]
	v_mfma_f32_16x16x32_bf16 v[28:31], v[158:161], v[202:205], v[28:31]
	v_mfma_f32_16x16x32_bf16 v[24:27], v[194:197], v[202:205], v[24:27]
	v_mfma_f32_16x16x32_bf16 v[20:23], v[158:161], v[210:213], v[20:23]
	v_mfma_f32_16x16x32_bf16 v[16:19], v[194:197], v[210:213], v[16:19]
	v_mfma_f32_16x16x32_bf16 v[12:15], v[158:161], v[218:221], v[12:15]
	v_mfma_f32_16x16x32_bf16 v[8:11], v[194:197], v[218:221], v[8:11]
	v_mfma_f32_16x16x32_bf16 v[4:7], v[158:161], v[226:229], v[4:7]
	v_mfma_f32_16x16x32_bf16 v[0:3], v[194:197], v[226:229], v[0:3]
	s_setprio 0
	s_barrier
	v_or_b32_e32 v138, 0x18000, v136
	v_add_u32_e32 v142, 0x18400, v136
	v_add_u32_e32 v146, 0x18800, v136
	v_add_u32_e32 v150, 0x18c00, v136
	v_or_b32_e32 v154, 0x1c000, v136
	v_add_u32_e32 v158, 0x1c400, v136
	v_add_u32_e32 v162, 0x1c800, v136
	ds_read_b128 v[138:141], v138
	ds_read_b128 v[142:145], v142
	ds_read_b128 v[146:149], v146
	ds_read_b128 v[150:153], v150
	ds_read_b128 v[154:157], v154
	ds_read_b128 v[158:161], v158
	v_add_u32_e32 v180, 0x1cc00, v136
	ds_read_b128 v[162:165], v162
	ds_read_b128 v[194:197], v180
	s_add_u32 s14, s14, s56
	s_addc_u32 s15, s15, 0
	s_mov_b32 m0, s94
	v_lshl_add_u64 v[240:241], s[14:15], 0, v[168:169]
	ds_read_b128 v[198:201], v137 offset:32768
	ds_read_b128 v[202:205], v137 offset:33792
	ds_read_b128 v[206:209], v137 offset:34816
	ds_read_b128 v[210:213], v137 offset:35840
	ds_read_b128 v[214:217], v137 offset:36864
	ds_read_b128 v[218:221], v137 offset:37888
	ds_read_b128 v[222:225], v137 offset:38912
	ds_read_b128 v[226:229], v137 offset:39936
	v_lshl_add_u64 v[240:241], s[14:15], 0, v[128:129]
	s_mov_b32 m0, vcc_lo
	s_nop 0
	s_waitcnt vmcnt(0)
	s_waitcnt lgkmcnt(0)
	s_barrier
	s_setprio 1
	s_waitcnt lgkmcnt(0)
	v_mfma_f32_16x16x32_bf16 v[124:127], v[138:141], v[198:201], v[124:127]
	v_mfma_f32_16x16x32_bf16 v[120:123], v[146:149], v[198:201], v[120:123]
	v_mfma_f32_16x16x32_bf16 v[116:119], v[138:141], v[206:209], v[116:119]
	v_mfma_f32_16x16x32_bf16 v[112:115], v[146:149], v[206:209], v[112:115]
	v_mfma_f32_16x16x32_bf16 v[108:111], v[138:141], v[214:217], v[108:111]
	v_mfma_f32_16x16x32_bf16 v[104:107], v[146:149], v[214:217], v[104:107]
	v_mfma_f32_16x16x32_bf16 v[100:103], v[138:141], v[222:225], v[100:103]
	v_mfma_f32_16x16x32_bf16 v[96:99], v[146:149], v[222:225], v[96:99]
	v_mfma_f32_16x16x32_bf16 v[124:127], v[142:145], v[202:205], v[124:127]
	v_mfma_f32_16x16x32_bf16 v[120:123], v[150:153], v[202:205], v[120:123]
	v_mfma_f32_16x16x32_bf16 v[116:119], v[142:145], v[210:213], v[116:119]
	v_mfma_f32_16x16x32_bf16 v[112:115], v[150:153], v[210:213], v[112:115]
	v_mfma_f32_16x16x32_bf16 v[108:111], v[142:145], v[218:221], v[108:111]
	v_mfma_f32_16x16x32_bf16 v[104:107], v[150:153], v[218:221], v[104:107]
	v_mfma_f32_16x16x32_bf16 v[100:103], v[142:145], v[226:229], v[100:103]
	v_mfma_f32_16x16x32_bf16 v[96:99], v[150:153], v[226:229], v[96:99]
	s_setprio 0
	s_setprio 1
	v_mfma_f32_16x16x32_bf16 v[92:95], v[154:157], v[198:201], v[92:95]
	v_mfma_f32_16x16x32_bf16 v[88:91], v[162:165], v[198:201], v[88:91]
	v_mfma_f32_16x16x32_bf16 v[84:87], v[154:157], v[206:209], v[84:87]
	v_mfma_f32_16x16x32_bf16 v[80:83], v[162:165], v[206:209], v[80:83]
	v_mfma_f32_16x16x32_bf16 v[76:79], v[154:157], v[214:217], v[76:79]
	v_mfma_f32_16x16x32_bf16 v[72:75], v[162:165], v[214:217], v[72:75]
	v_mfma_f32_16x16x32_bf16 v[68:71], v[154:157], v[222:225], v[68:71]
	v_mfma_f32_16x16x32_bf16 v[64:67], v[162:165], v[222:225], v[64:67]
	v_mfma_f32_16x16x32_bf16 v[92:95], v[158:161], v[202:205], v[92:95]
	v_mfma_f32_16x16x32_bf16 v[88:91], v[194:197], v[202:205], v[88:91]
	v_mfma_f32_16x16x32_bf16 v[84:87], v[158:161], v[210:213], v[84:87]
	v_mfma_f32_16x16x32_bf16 v[80:83], v[194:197], v[210:213], v[80:83]
	v_mfma_f32_16x16x32_bf16 v[76:79], v[158:161], v[218:221], v[76:79]
	v_mfma_f32_16x16x32_bf16 v[72:75], v[194:197], v[218:221], v[72:75]
	v_mfma_f32_16x16x32_bf16 v[68:71], v[158:161], v[226:229], v[68:71]
	v_mfma_f32_16x16x32_bf16 v[64:67], v[194:197], v[226:229], v[64:67]
	s_setprio 0
	s_barrier
	s_mov_b32 m0, s17
	v_lshl_add_u64 v[166:167], v[166:167], 0, s[34:35]
	ds_read_b128 v[198:201], v137 offset:49152
	ds_read_b128 v[202:205], v137 offset:50176
	ds_read_b128 v[206:209], v137 offset:51200
	ds_read_b128 v[210:213], v137 offset:52224
	ds_read_b128 v[214:217], v137 offset:53248
	ds_read_b128 v[218:221], v137 offset:54272
	ds_read_b128 v[222:225], v137 offset:55296
	ds_read_b128 v[226:229], v137 offset:56320
	v_lshl_add_u64 v[166:167], v[230:231], 0, s[34:35]
	s_mov_b32 m0, s24
	s_nop 0
	v_lshl_add_u64 v[166:167], v[232:233], 0, s[34:35]
	s_mov_b32 m0, s97
	s_nop 0
	v_lshl_add_u64 v[166:167], v[234:235], 0, s[34:35]
	s_mov_b32 m0, vcc_hi
	s_nop 0
	v_lshl_add_u64 v[166:167], v[236:237], 0, s[34:35]
	s_mov_b32 m0, s60
	s_nop 0
	v_lshl_add_u64 v[166:167], v[238:239], 0, s[34:35]
	s_mov_b32 m0, s96
	s_nop 0
	s_waitcnt vmcnt(0)
	s_waitcnt lgkmcnt(0)
	s_barrier
	s_setprio 1
	s_waitcnt lgkmcnt(0)
	v_mfma_f32_16x16x32_bf16 v[60:63], v[138:141], v[198:201], v[60:63]
	v_mfma_f32_16x16x32_bf16 v[56:59], v[146:149], v[198:201], v[56:59]
	v_mfma_f32_16x16x32_bf16 v[52:55], v[138:141], v[206:209], v[52:55]
	v_mfma_f32_16x16x32_bf16 v[48:51], v[146:149], v[206:209], v[48:51]
	v_mfma_f32_16x16x32_bf16 v[44:47], v[138:141], v[214:217], v[44:47]
	v_mfma_f32_16x16x32_bf16 v[40:43], v[146:149], v[214:217], v[40:43]
	v_mfma_f32_16x16x32_bf16 v[36:39], v[138:141], v[222:225], v[36:39]
	v_mfma_f32_16x16x32_bf16 v[32:35], v[146:149], v[222:225], v[32:35]
	v_mfma_f32_16x16x32_bf16 v[60:63], v[142:145], v[202:205], v[60:63]
	v_mfma_f32_16x16x32_bf16 v[56:59], v[150:153], v[202:205], v[56:59]
	v_mfma_f32_16x16x32_bf16 v[52:55], v[142:145], v[210:213], v[52:55]
	v_mfma_f32_16x16x32_bf16 v[48:51], v[150:153], v[210:213], v[48:51]
	v_mfma_f32_16x16x32_bf16 v[44:47], v[142:145], v[218:221], v[44:47]
	v_mfma_f32_16x16x32_bf16 v[40:43], v[150:153], v[218:221], v[40:43]
	v_mfma_f32_16x16x32_bf16 v[36:39], v[142:145], v[226:229], v[36:39]
	v_mfma_f32_16x16x32_bf16 v[32:35], v[150:153], v[226:229], v[32:35]
	s_setprio 0
	s_setprio 1
	v_mfma_f32_16x16x32_bf16 v[28:31], v[154:157], v[198:201], v[28:31]
	v_mfma_f32_16x16x32_bf16 v[24:27], v[162:165], v[198:201], v[24:27]
	v_mfma_f32_16x16x32_bf16 v[20:23], v[154:157], v[206:209], v[20:23]
	v_mfma_f32_16x16x32_bf16 v[16:19], v[162:165], v[206:209], v[16:19]
	v_mfma_f32_16x16x32_bf16 v[12:15], v[154:157], v[214:217], v[12:15]
	v_mfma_f32_16x16x32_bf16 v[8:11], v[162:165], v[214:217], v[8:11]
	v_mfma_f32_16x16x32_bf16 v[4:7], v[154:157], v[222:225], v[4:7]
	v_mfma_f32_16x16x32_bf16 v[0:3], v[162:165], v[222:225], v[0:3]
	v_mfma_f32_16x16x32_bf16 v[28:31], v[158:161], v[202:205], v[28:31]
	v_mfma_f32_16x16x32_bf16 v[24:27], v[194:197], v[202:205], v[24:27]
	v_mfma_f32_16x16x32_bf16 v[20:23], v[158:161], v[210:213], v[20:23]
	v_mfma_f32_16x16x32_bf16 v[16:19], v[194:197], v[210:213], v[16:19]
	v_mfma_f32_16x16x32_bf16 v[12:15], v[158:161], v[218:221], v[12:15]
	v_mfma_f32_16x16x32_bf16 v[8:11], v[194:197], v[218:221], v[8:11]
	v_mfma_f32_16x16x32_bf16 v[4:7], v[158:161], v[226:229], v[4:7]
	v_mfma_f32_16x16x32_bf16 v[0:3], v[194:197], v[226:229], v[0:3]
	s_setprio 0
	s_barrier
	s_cmp_lt_u32 s36, s62
	s_mov_b64 s[26:27], s[48:49]
	s_mov_b32 s14, s36
	s_waitcnt vmcnt(0)
	s_cmpk_gt_u32 s89, 0xff
	s_cbranch_scc1 .LBB0_79
	s_barrier

.LBB0_210:
	s_add_u32 s14, s60, s44
	s_addc_u32 s15, s91, s45
	v_or_b32_e32 v138, 0x10000, v136
	v_add_u32_e32 v142, 0x10400, v136
	v_add_u32_e32 v146, 0x10800, v136
	v_add_u32_e32 v150, 0x10c00, v136
	v_or_b32_e32 v154, 0x14000, v136
	v_add_u32_e32 v158, 0x14400, v136
	v_add_u32_e32 v162, 0x14800, v136
	s_add_u32 s14, s14, 0x4000100
	ds_read_b128 v[138:141], v138
	ds_read_b128 v[142:145], v142
	ds_read_b128 v[146:149], v146
	ds_read_b128 v[150:153], v150
	ds_read_b128 v[154:157], v154
	ds_read_b128 v[158:161], v158
	v_add_u32_e32 v166, 0x14c00, v136
	ds_read_b128 v[162:165], v162
	ds_read_b128 v[194:197], v166
	s_addc_u32 s15, s15, 0
	s_add_u32 s36, s92, s44
	s_addc_u32 s37, s93, s45
	s_cmpk_eq_i32 s44, 0x700
	s_cselect_b32 s27, s43, s15
	s_cselect_b32 s26, s42, s14
	s_cselect_b32 s15, s41, s37
	s_cselect_b32 s14, s40, s36
	v_lshl_add_u64 v[166:167], v[130:131], 0, s[44:45]
	s_add_i32 m0, s16, 0xc000
	ds_read_b128 v[198:201], v137
	ds_read_b128 v[202:205], v137 offset:1024
	ds_read_b128 v[206:209], v137 offset:2048
	ds_read_b128 v[210:213], v137 offset:3072
	ds_read_b128 v[214:217], v137 offset:4096
	ds_read_b128 v[218:221], v137 offset:5120
	ds_read_b128 v[222:225], v137 offset:6144
	ds_read_b128 v[226:229], v137 offset:7168
	global_load_lds_dwordx4 v[166:167], off
	v_lshl_add_u64 v[166:167], v[132:133], 0, s[44:45]
	s_add_i32 m0, s16, 0xe000
	s_nop 0
	global_load_lds_dwordx4 v[166:167], off
	s_waitcnt vmcnt(8)
	s_waitcnt lgkmcnt(0)
	s_barrier
	s_setprio 1
	s_waitcnt lgkmcnt(0)
	v_mfma_f32_16x16x32_bf16 v[124:127], v[138:141], v[198:201], v[124:127]
	v_mfma_f32_16x16x32_bf16 v[120:123], v[146:149], v[198:201], v[120:123]
	v_mfma_f32_16x16x32_bf16 v[116:119], v[138:141], v[206:209], v[116:119]
	v_mfma_f32_16x16x32_bf16 v[112:115], v[146:149], v[206:209], v[112:115]
	v_mfma_f32_16x16x32_bf16 v[108:111], v[138:141], v[214:217], v[108:111]
	v_mfma_f32_16x16x32_bf16 v[104:107], v[146:149], v[214:217], v[104:107]
	v_mfma_f32_16x16x32_bf16 v[100:103], v[138:141], v[222:225], v[100:103]
	v_mfma_f32_16x16x32_bf16 v[96:99], v[146:149], v[222:225], v[96:99]
	v_mfma_f32_16x16x32_bf16 v[124:127], v[142:145], v[202:205], v[124:127]
	v_mfma_f32_16x16x32_bf16 v[120:123], v[150:153], v[202:205], v[120:123]
	v_mfma_f32_16x16x32_bf16 v[116:119], v[142:145], v[210:213], v[116:119]
	v_mfma_f32_16x16x32_bf16 v[112:115], v[150:153], v[210:213], v[112:115]
	v_mfma_f32_16x16x32_bf16 v[108:111], v[142:145], v[218:221], v[108:111]
	v_mfma_f32_16x16x32_bf16 v[104:107], v[150:153], v[218:221], v[104:107]
	v_mfma_f32_16x16x32_bf16 v[100:103], v[142:145], v[226:229], v[100:103]
	v_mfma_f32_16x16x32_bf16 v[96:99], v[150:153], v[226:229], v[96:99]
	s_setprio 0
	s_setprio 1
	v_mfma_f32_16x16x32_bf16 v[92:95], v[154:157], v[198:201], v[92:95]
	v_mfma_f32_16x16x32_bf16 v[88:91], v[162:165], v[198:201], v[88:91]
	v_mfma_f32_16x16x32_bf16 v[84:87], v[154:157], v[206:209], v[84:87]
	v_mfma_f32_16x16x32_bf16 v[80:83], v[162:165], v[206:209], v[80:83]
	v_mfma_f32_16x16x32_bf16 v[76:79], v[154:157], v[214:217], v[76:79]
	v_mfma_f32_16x16x32_bf16 v[72:75], v[162:165], v[214:217], v[72:75]
	v_mfma_f32_16x16x32_bf16 v[68:71], v[154:157], v[222:225], v[68:71]
	v_mfma_f32_16x16x32_bf16 v[64:67], v[162:165], v[222:225], v[64:67]
	v_mfma_f32_16x16x32_bf16 v[92:95], v[158:161], v[202:205], v[92:95]
	v_mfma_f32_16x16x32_bf16 v[88:91], v[194:197], v[202:205], v[88:91]
	v_mfma_f32_16x16x32_bf16 v[84:87], v[158:161], v[210:213], v[84:87]
	v_mfma_f32_16x16x32_bf16 v[80:83], v[194:197], v[210:213], v[80:83]
	v_mfma_f32_16x16x32_bf16 v[76:79], v[158:161], v[218:221], v[76:79]
	v_mfma_f32_16x16x32_bf16 v[72:75], v[194:197], v[218:221], v[72:75]
	v_mfma_f32_16x16x32_bf16 v[68:71], v[158:161], v[226:229], v[68:71]
	v_mfma_f32_16x16x32_bf16 v[64:67], v[194:197], v[226:229], v[64:67]
	s_setprio 0
	s_barrier
	s_mov_b32 m0, s17
	v_lshl_add_u64 v[166:167], s[14:15], 0, v[168:169]
	s_add_u32 s36, s14, 0x40000
	ds_read_b128 v[198:201], v137 offset:16384
	ds_read_b128 v[202:205], v137 offset:17408
	ds_read_b128 v[206:209], v137 offset:18432
	ds_read_b128 v[210:213], v137 offset:19456
	ds_read_b128 v[214:217], v137 offset:20480
	ds_read_b128 v[218:221], v137 offset:21504
	ds_read_b128 v[222:225], v137 offset:22528
	ds_read_b128 v[226:229], v137 offset:23552
	global_load_lds_dwordx4 v[166:167], off
	v_lshl_add_u64 v[230:231], s[14:15], 0, v[128:129]
	s_mov_b32 m0, s28
	s_addc_u32 s37, s15, 0
	global_load_lds_dwordx4 v[230:231], off
	v_lshl_add_u64 v[232:233], s[36:37], 0, v[168:169]
	s_mov_b32 m0, s29
	v_lshl_add_u64 v[234:235], s[26:27], 0, v[128:129]
	global_load_lds_dwordx4 v[232:233], off
	v_lshl_add_u64 v[232:233], s[36:37], 0, v[128:129]
	s_mov_b32 m0, s46
	s_nop 0
	global_load_lds_dwordx4 v[232:233], off
	v_lshl_add_u64 v[232:233], s[26:27], 0, v[168:169]
	s_mov_b32 m0, s16
	s_nop 0
	global_load_lds_dwordx4 v[232:233], off
	s_mov_b32 m0, s47
	s_nop 0
	global_load_lds_dwordx4 v[234:235], off
	s_waitcnt vmcnt(8)
	s_waitcnt lgkmcnt(0)
	s_barrier
	s_setprio 1
	s_waitcnt lgkmcnt(0)
	v_mfma_f32_16x16x32_bf16 v[60:63], v[138:141], v[198:201], v[60:63]
	v_mfma_f32_16x16x32_bf16 v[56:59], v[146:149], v[198:201], v[56:59]
	v_mfma_f32_16x16x32_bf16 v[52:55], v[138:141], v[206:209], v[52:55]
	v_mfma_f32_16x16x32_bf16 v[48:51], v[146:149], v[206:209], v[48:51]
	v_mfma_f32_16x16x32_bf16 v[44:47], v[138:141], v[214:217], v[44:47]
	v_mfma_f32_16x16x32_bf16 v[40:43], v[146:149], v[214:217], v[40:43]
	v_mfma_f32_16x16x32_bf16 v[36:39], v[138:141], v[222:225], v[36:39]
	v_mfma_f32_16x16x32_bf16 v[32:35], v[146:149], v[222:225], v[32:35]
	v_mfma_f32_16x16x32_bf16 v[60:63], v[142:145], v[202:205], v[60:63]
	v_mfma_f32_16x16x32_bf16 v[56:59], v[150:153], v[202:205], v[56:59]
	v_mfma_f32_16x16x32_bf16 v[52:55], v[142:145], v[210:213], v[52:55]
	v_mfma_f32_16x16x32_bf16 v[48:51], v[150:153], v[210:213], v[48:51]
	v_mfma_f32_16x16x32_bf16 v[44:47], v[142:145], v[218:221], v[44:47]
	v_mfma_f32_16x16x32_bf16 v[40:43], v[150:153], v[218:221], v[40:43]
	v_mfma_f32_16x16x32_bf16 v[36:39], v[142:145], v[226:229], v[36:39]
	v_mfma_f32_16x16x32_bf16 v[32:35], v[150:153], v[226:229], v[32:35]
	s_setprio 0
	s_setprio 1
	v_mfma_f32_16x16x32_bf16 v[28:31], v[154:157], v[198:201], v[28:31]
	v_mfma_f32_16x16x32_bf16 v[24:27], v[162:165], v[198:201], v[24:27]
	v_mfma_f32_16x16x32_bf16 v[20:23], v[154:157], v[206:209], v[20:23]
	v_mfma_f32_16x16x32_bf16 v[16:19], v[162:165], v[206:209], v[16:19]
	v_mfma_f32_16x16x32_bf16 v[12:15], v[154:157], v[214:217], v[12:15]
	v_mfma_f32_16x16x32_bf16 v[8:11], v[162:165], v[214:217], v[8:11]
	v_mfma_f32_16x16x32_bf16 v[4:7], v[154:157], v[222:225], v[4:7]
	v_mfma_f32_16x16x32_bf16 v[0:3], v[162:165], v[222:225], v[0:3]
	v_mfma_f32_16x16x32_bf16 v[28:31], v[158:161], v[202:205], v[28:31]
	v_mfma_f32_16x16x32_bf16 v[24:27], v[194:197], v[202:205], v[24:27]
	v_mfma_f32_16x16x32_bf16 v[20:23], v[158:161], v[210:213], v[20:23]
	v_mfma_f32_16x16x32_bf16 v[16:19], v[194:197], v[210:213], v[16:19]
	v_mfma_f32_16x16x32_bf16 v[12:15], v[158:161], v[218:221], v[12:15]
	v_mfma_f32_16x16x32_bf16 v[8:11], v[194:197], v[218:221], v[8:11]
	v_mfma_f32_16x16x32_bf16 v[4:7], v[158:161], v[226:229], v[4:7]
	v_mfma_f32_16x16x32_bf16 v[0:3], v[194:197], v[226:229], v[0:3]
	s_setprio 0
	s_barrier
	v_or_b32_e32 v138, 0x18000, v136
	v_add_u32_e32 v142, 0x18400, v136
	v_add_u32_e32 v146, 0x18800, v136
	v_add_u32_e32 v150, 0x18c00, v136
	v_or_b32_e32 v154, 0x1c000, v136
	v_add_u32_e32 v158, 0x1c400, v136
	v_add_u32_e32 v162, 0x1c800, v136
	ds_read_b128 v[138:141], v138
	ds_read_b128 v[142:145], v142
	ds_read_b128 v[146:149], v146
	ds_read_b128 v[150:153], v150
	ds_read_b128 v[154:157], v154
	ds_read_b128 v[158:161], v158
	v_add_u32_e32 v180, 0x1cc00, v136
	ds_read_b128 v[162:165], v162
	ds_read_b128 v[194:197], v180
	s_add_u32 s26, s26, 0x40000
	s_addc_u32 s27, s27, 0
	s_mov_b32 m0, s49
	v_lshl_add_u64 v[236:237], s[26:27], 0, v[168:169]
	ds_read_b128 v[198:201], v137 offset:32768
	ds_read_b128 v[202:205], v137 offset:33792
	ds_read_b128 v[206:209], v137 offset:34816
	ds_read_b128 v[210:213], v137 offset:35840
	ds_read_b128 v[214:217], v137 offset:36864
	ds_read_b128 v[218:221], v137 offset:37888
	ds_read_b128 v[222:225], v137 offset:38912
	ds_read_b128 v[226:229], v137 offset:39936
	global_load_lds_dwordx4 v[236:237], off
	v_lshl_add_u64 v[236:237], s[26:27], 0, v[128:129]
	s_mov_b32 m0, s54
	s_nop 0
	global_load_lds_dwordx4 v[236:237], off
	s_waitcnt vmcnt(8)
	s_waitcnt lgkmcnt(0)
	s_barrier
	s_setprio 1
	s_waitcnt lgkmcnt(0)
	v_mfma_f32_16x16x32_bf16 v[124:127], v[138:141], v[198:201], v[124:127]
	v_mfma_f32_16x16x32_bf16 v[120:123], v[146:149], v[198:201], v[120:123]
	v_mfma_f32_16x16x32_bf16 v[116:119], v[138:141], v[206:209], v[116:119]
	v_mfma_f32_16x16x32_bf16 v[112:115], v[146:149], v[206:209], v[112:115]
	v_mfma_f32_16x16x32_bf16 v[108:111], v[138:141], v[214:217], v[108:111]
	v_mfma_f32_16x16x32_bf16 v[104:107], v[146:149], v[214:217], v[104:107]
	v_mfma_f32_16x16x32_bf16 v[100:103], v[138:141], v[222:225], v[100:103]
	v_mfma_f32_16x16x32_bf16 v[96:99], v[146:149], v[222:225], v[96:99]
	v_mfma_f32_16x16x32_bf16 v[124:127], v[142:145], v[202:205], v[124:127]
	v_mfma_f32_16x16x32_bf16 v[120:123], v[150:153], v[202:205], v[120:123]
	v_mfma_f32_16x16x32_bf16 v[116:119], v[142:145], v[210:213], v[116:119]
	v_mfma_f32_16x16x32_bf16 v[112:115], v[150:153], v[210:213], v[112:115]
	v_mfma_f32_16x16x32_bf16 v[108:111], v[142:145], v[218:221], v[108:111]
	v_mfma_f32_16x16x32_bf16 v[104:107], v[150:153], v[218:221], v[104:107]
	v_mfma_f32_16x16x32_bf16 v[100:103], v[142:145], v[226:229], v[100:103]
	v_mfma_f32_16x16x32_bf16 v[96:99], v[150:153], v[226:229], v[96:99]
	s_setprio 0
	s_setprio 1
	v_mfma_f32_16x16x32_bf16 v[92:95], v[154:157], v[198:201], v[92:95]
	v_mfma_f32_16x16x32_bf16 v[88:91], v[162:165], v[198:201], v[88:91]
	v_mfma_f32_16x16x32_bf16 v[84:87], v[154:157], v[206:209], v[84:87]
	v_mfma_f32_16x16x32_bf16 v[80:83], v[162:165], v[206:209], v[80:83]
	v_mfma_f32_16x16x32_bf16 v[76:79], v[154:157], v[214:217], v[76:79]
	v_mfma_f32_16x16x32_bf16 v[72:75], v[162:165], v[214:217], v[72:75]
	v_mfma_f32_16x16x32_bf16 v[68:71], v[154:157], v[222:225], v[68:71]
	v_mfma_f32_16x16x32_bf16 v[64:67], v[162:165], v[222:225], v[64:67]
	v_mfma_f32_16x16x32_bf16 v[92:95], v[158:161], v[202:205], v[92:95]
	v_mfma_f32_16x16x32_bf16 v[88:91], v[194:197], v[202:205], v[88:91]
	v_mfma_f32_16x16x32_bf16 v[84:87], v[158:161], v[210:213], v[84:87]
	v_mfma_f32_16x16x32_bf16 v[80:83], v[194:197], v[210:213], v[80:83]
	v_mfma_f32_16x16x32_bf16 v[76:79], v[158:161], v[218:221], v[76:79]
	v_mfma_f32_16x16x32_bf16 v[72:75], v[194:197], v[218:221], v[72:75]
	v_mfma_f32_16x16x32_bf16 v[68:71], v[158:161], v[226:229], v[68:71]
	v_mfma_f32_16x16x32_bf16 v[64:67], v[194:197], v[226:229], v[64:67]
	s_setprio 0
	s_barrier
	s_mov_b32 m0, s56
	v_lshl_add_u64 v[166:167], v[166:167], 0, s[34:35]
	s_add_u32 s14, s14, 0x40080
	ds_read_b128 v[198:201], v137 offset:49152
	ds_read_b128 v[202:205], v137 offset:50176
	ds_read_b128 v[206:209], v137 offset:51200
	ds_read_b128 v[210:213], v137 offset:52224
	ds_read_b128 v[214:217], v137 offset:53248
	ds_read_b128 v[218:221], v137 offset:54272
	ds_read_b128 v[222:225], v137 offset:55296
	ds_read_b128 v[226:229], v137 offset:56320
	global_load_lds_dwordx4 v[166:167], off
	v_lshl_add_u64 v[166:167], v[230:231], 0, s[34:35]
	s_mov_b32 m0, s85
	s_addc_u32 s15, s15, 0
	global_load_lds_dwordx4 v[166:167], off
	v_lshl_add_u64 v[166:167], s[14:15], 0, v[168:169]
	s_mov_b32 m0, s90
	s_nop 0
	global_load_lds_dwordx4 v[166:167], off
	v_lshl_add_u64 v[166:167], s[14:15], 0, v[128:129]
	s_mov_b32 m0, s24
	s_nop 0
	global_load_lds_dwordx4 v[166:167], off
	v_lshl_add_u64 v[166:167], v[232:233], 0, s[34:35]
	s_mov_b32 m0, s86
	s_nop 0
	global_load_lds_dwordx4 v[166:167], off
	v_lshl_add_u64 v[166:167], v[234:235], 0, s[34:35]
	s_mov_b32 m0, s87
	s_nop 0
	global_load_lds_dwordx4 v[166:167], off
	s_waitcnt vmcnt(8)
	s_waitcnt lgkmcnt(0)
	s_barrier
	s_setprio 1
	s_waitcnt lgkmcnt(0)
	v_mfma_f32_16x16x32_bf16 v[60:63], v[138:141], v[198:201], v[60:63]
	v_mfma_f32_16x16x32_bf16 v[56:59], v[146:149], v[198:201], v[56:59]
	v_mfma_f32_16x16x32_bf16 v[52:55], v[138:141], v[206:209], v[52:55]
	v_mfma_f32_16x16x32_bf16 v[48:51], v[146:149], v[206:209], v[48:51]
	v_mfma_f32_16x16x32_bf16 v[44:47], v[138:141], v[214:217], v[44:47]
	v_mfma_f32_16x16x32_bf16 v[40:43], v[146:149], v[214:217], v[40:43]
	v_mfma_f32_16x16x32_bf16 v[36:39], v[138:141], v[222:225], v[36:39]
	v_mfma_f32_16x16x32_bf16 v[32:35], v[146:149], v[222:225], v[32:35]
	v_mfma_f32_16x16x32_bf16 v[60:63], v[142:145], v[202:205], v[60:63]
	v_mfma_f32_16x16x32_bf16 v[56:59], v[150:153], v[202:205], v[56:59]
	v_mfma_f32_16x16x32_bf16 v[52:55], v[142:145], v[210:213], v[52:55]
	v_mfma_f32_16x16x32_bf16 v[48:51], v[150:153], v[210:213], v[48:51]
	v_mfma_f32_16x16x32_bf16 v[44:47], v[142:145], v[218:221], v[44:47]
	v_mfma_f32_16x16x32_bf16 v[40:43], v[150:153], v[218:221], v[40:43]
	v_mfma_f32_16x16x32_bf16 v[36:39], v[142:145], v[226:229], v[36:39]
	v_mfma_f32_16x16x32_bf16 v[32:35], v[150:153], v[226:229], v[32:35]
	s_setprio 0
	s_setprio 1
	v_mfma_f32_16x16x32_bf16 v[28:31], v[154:157], v[198:201], v[28:31]
	v_mfma_f32_16x16x32_bf16 v[24:27], v[162:165], v[198:201], v[24:27]
	v_mfma_f32_16x16x32_bf16 v[20:23], v[154:157], v[206:209], v[20:23]
	v_mfma_f32_16x16x32_bf16 v[16:19], v[162:165], v[206:209], v[16:19]
	v_mfma_f32_16x16x32_bf16 v[12:15], v[154:157], v[214:217], v[12:15]
	v_mfma_f32_16x16x32_bf16 v[8:11], v[162:165], v[214:217], v[8:11]
	v_mfma_f32_16x16x32_bf16 v[4:7], v[154:157], v[222:225], v[4:7]
	v_mfma_f32_16x16x32_bf16 v[0:3], v[162:165], v[222:225], v[0:3]
	v_mfma_f32_16x16x32_bf16 v[28:31], v[158:161], v[202:205], v[28:31]
	v_mfma_f32_16x16x32_bf16 v[24:27], v[194:197], v[202:205], v[24:27]
	v_mfma_f32_16x16x32_bf16 v[20:23], v[158:161], v[210:213], v[20:23]
	v_mfma_f32_16x16x32_bf16 v[16:19], v[194:197], v[210:213], v[16:19]
	v_mfma_f32_16x16x32_bf16 v[12:15], v[158:161], v[218:221], v[12:15]
	v_mfma_f32_16x16x32_bf16 v[8:11], v[194:197], v[218:221], v[8:11]
	v_mfma_f32_16x16x32_bf16 v[4:7], v[158:161], v[226:229], v[4:7]
	v_mfma_f32_16x16x32_bf16 v[0:3], v[194:197], v[226:229], v[0:3]
	s_setprio 0
	s_add_i32 s94, s94, 2
	s_add_u32 s44, s44, 0x100
	s_addc_u32 s45, s45, 0
	s_cmp_lt_u32 s94, 12
	s_barrier
	s_cbranch_scc1 .LBB0_210
	s_add_u32 s14, s60, s44
	s_addc_u32 s15, s91, s45
	v_or_b32_e32 v138, 0x10000, v136
	v_add_u32_e32 v142, 0x10400, v136
	v_add_u32_e32 v146, 0x10800, v136
	v_add_u32_e32 v150, 0x10c00, v136
	v_or_b32_e32 v154, 0x14000, v136
	v_add_u32_e32 v158, 0x14400, v136
	v_add_u32_e32 v162, 0x14800, v136
	s_add_u32 s14, s14, 0x4000100
	ds_read_b128 v[138:141], v138
	ds_read_b128 v[142:145], v142
	ds_read_b128 v[146:149], v146
	ds_read_b128 v[150:153], v150
	ds_read_b128 v[154:157], v154
	ds_read_b128 v[158:161], v158
	v_add_u32_e32 v166, 0x14c00, v136
	ds_read_b128 v[162:165], v162
	ds_read_b128 v[194:197], v166
	s_addc_u32 s15, s15, 0
	s_add_u32 s36, s92, s44
	s_addc_u32 s37, s93, s45
	s_cmpk_eq_i32 s44, 0x700
	s_cselect_b32 s27, s43, s15
	s_cselect_b32 s26, s42, s14
	s_cselect_b32 s15, s41, s37
	s_cselect_b32 s14, s40, s36
	v_lshl_add_u64 v[166:167], v[130:131], 0, s[44:45]
	s_add_i32 m0, s16, 0xc000
	ds_read_b128 v[198:201], v137
	ds_read_b128 v[202:205], v137 offset:1024
	ds_read_b128 v[206:209], v137 offset:2048
	ds_read_b128 v[210:213], v137 offset:3072
	ds_read_b128 v[214:217], v137 offset:4096
	ds_read_b128 v[218:221], v137 offset:5120
	ds_read_b128 v[222:225], v137 offset:6144
	ds_read_b128 v[226:229], v137 offset:7168
	global_load_lds_dwordx4 v[166:167], off
	v_lshl_add_u64 v[166:167], v[132:133], 0, s[44:45]
	s_add_i32 m0, s16, 0xe000
	s_nop 0
	global_load_lds_dwordx4 v[166:167], off
	s_waitcnt vmcnt(8)
	s_waitcnt lgkmcnt(0)
	s_barrier
	s_setprio 1
	s_waitcnt lgkmcnt(0)
	v_mfma_f32_16x16x32_bf16 v[124:127], v[138:141], v[198:201], v[124:127]
	v_mfma_f32_16x16x32_bf16 v[120:123], v[146:149], v[198:201], v[120:123]
	v_mfma_f32_16x16x32_bf16 v[116:119], v[138:141], v[206:209], v[116:119]
	v_mfma_f32_16x16x32_bf16 v[112:115], v[146:149], v[206:209], v[112:115]
	v_mfma_f32_16x16x32_bf16 v[108:111], v[138:141], v[214:217], v[108:111]
	v_mfma_f32_16x16x32_bf16 v[104:107], v[146:149], v[214:217], v[104:107]
	v_mfma_f32_16x16x32_bf16 v[100:103], v[138:141], v[222:225], v[100:103]
	v_mfma_f32_16x16x32_bf16 v[96:99], v[146:149], v[222:225], v[96:99]
	v_mfma_f32_16x16x32_bf16 v[124:127], v[142:145], v[202:205], v[124:127]
	v_mfma_f32_16x16x32_bf16 v[120:123], v[150:153], v[202:205], v[120:123]
	v_mfma_f32_16x16x32_bf16 v[116:119], v[142:145], v[210:213], v[116:119]
	v_mfma_f32_16x16x32_bf16 v[112:115], v[150:153], v[210:213], v[112:115]
	v_mfma_f32_16x16x32_bf16 v[108:111], v[142:145], v[218:221], v[108:111]
	v_mfma_f32_16x16x32_bf16 v[104:107], v[150:153], v[218:221], v[104:107]
	v_mfma_f32_16x16x32_bf16 v[100:103], v[142:145], v[226:229], v[100:103]
	v_mfma_f32_16x16x32_bf16 v[96:99], v[150:153], v[226:229], v[96:99]
	s_setprio 0
	s_setprio 1
	v_mfma_f32_16x16x32_bf16 v[92:95], v[154:157], v[198:201], v[92:95]
	v_mfma_f32_16x16x32_bf16 v[88:91], v[162:165], v[198:201], v[88:91]
	v_mfma_f32_16x16x32_bf16 v[84:87], v[154:157], v[206:209], v[84:87]
	v_mfma_f32_16x16x32_bf16 v[80:83], v[162:165], v[206:209], v[80:83]
	v_mfma_f32_16x16x32_bf16 v[76:79], v[154:157], v[214:217], v[76:79]
	v_mfma_f32_16x16x32_bf16 v[72:75], v[162:165], v[214:217], v[72:75]
	v_mfma_f32_16x16x32_bf16 v[68:71], v[154:157], v[222:225], v[68:71]
	v_mfma_f32_16x16x32_bf16 v[64:67], v[162:165], v[222:225], v[64:67]
	v_mfma_f32_16x16x32_bf16 v[92:95], v[158:161], v[202:205], v[92:95]
	v_mfma_f32_16x16x32_bf16 v[88:91], v[194:197], v[202:205], v[88:91]
	v_mfma_f32_16x16x32_bf16 v[84:87], v[158:161], v[210:213], v[84:87]
	v_mfma_f32_16x16x32_bf16 v[80:83], v[194:197], v[210:213], v[80:83]
	v_mfma_f32_16x16x32_bf16 v[76:79], v[158:161], v[218:221], v[76:79]
	v_mfma_f32_16x16x32_bf16 v[72:75], v[194:197], v[218:221], v[72:75]
	v_mfma_f32_16x16x32_bf16 v[68:71], v[158:161], v[226:229], v[68:71]
	v_mfma_f32_16x16x32_bf16 v[64:67], v[194:197], v[226:229], v[64:67]
	s_setprio 0
	s_barrier
	s_mov_b32 m0, s17
	v_lshl_add_u64 v[166:167], s[14:15], 0, v[168:169]
	s_add_u32 s36, s14, 0x40000
	ds_read_b128 v[198:201], v137 offset:16384
	ds_read_b128 v[202:205], v137 offset:17408
	ds_read_b128 v[206:209], v137 offset:18432
	ds_read_b128 v[210:213], v137 offset:19456
	ds_read_b128 v[214:217], v137 offset:20480
	ds_read_b128 v[218:221], v137 offset:21504
	ds_read_b128 v[222:225], v137 offset:22528
	ds_read_b128 v[226:229], v137 offset:23552
	v_lshl_add_u64 v[230:231], s[14:15], 0, v[128:129]
	s_mov_b32 m0, s28
	s_addc_u32 s37, s15, 0
	v_lshl_add_u64 v[232:233], s[36:37], 0, v[168:169]
	s_mov_b32 m0, s29
	v_lshl_add_u64 v[234:235], s[26:27], 0, v[128:129]
	v_lshl_add_u64 v[232:233], s[36:37], 0, v[128:129]
	s_mov_b32 m0, s46
	s_nop 0
	v_lshl_add_u64 v[232:233], s[26:27], 0, v[168:169]
	s_mov_b32 m0, s16
	s_nop 0
	s_mov_b32 m0, s47
	s_nop 0
	s_waitcnt vmcnt(2)
	s_waitcnt lgkmcnt(0)
	s_barrier
	s_setprio 1
	s_waitcnt lgkmcnt(0)
	v_mfma_f32_16x16x32_bf16 v[60:63], v[138:141], v[198:201], v[60:63]
	v_mfma_f32_16x16x32_bf16 v[56:59], v[146:149], v[198:201], v[56:59]
	v_mfma_f32_16x16x32_bf16 v[52:55], v[138:141], v[206:209], v[52:55]
	v_mfma_f32_16x16x32_bf16 v[48:51], v[146:149], v[206:209], v[48:51]
	v_mfma_f32_16x16x32_bf16 v[44:47], v[138:141], v[214:217], v[44:47]
	v_mfma_f32_16x16x32_bf16 v[40:43], v[146:149], v[214:217], v[40:43]
	v_mfma_f32_16x16x32_bf16 v[36:39], v[138:141], v[222:225], v[36:39]
	v_mfma_f32_16x16x32_bf16 v[32:35], v[146:149], v[222:225], v[32:35]
	v_mfma_f32_16x16x32_bf16 v[60:63], v[142:145], v[202:205], v[60:63]
	v_mfma_f32_16x16x32_bf16 v[56:59], v[150:153], v[202:205], v[56:59]
	v_mfma_f32_16x16x32_bf16 v[52:55], v[142:145], v[210:213], v[52:55]
	v_mfma_f32_16x16x32_bf16 v[48:51], v[150:153], v[210:213], v[48:51]
	v_mfma_f32_16x16x32_bf16 v[44:47], v[142:145], v[218:221], v[44:47]
	v_mfma_f32_16x16x32_bf16 v[40:43], v[150:153], v[218:221], v[40:43]
	v_mfma_f32_16x16x32_bf16 v[36:39], v[142:145], v[226:229], v[36:39]
	v_mfma_f32_16x16x32_bf16 v[32:35], v[150:153], v[226:229], v[32:35]
	s_setprio 0
	s_setprio 1
	v_mfma_f32_16x16x32_bf16 v[28:31], v[154:157], v[198:201], v[28:31]
	v_mfma_f32_16x16x32_bf16 v[24:27], v[162:165], v[198:201], v[24:27]
	v_mfma_f32_16x16x32_bf16 v[20:23], v[154:157], v[206:209], v[20:23]
	v_mfma_f32_16x16x32_bf16 v[16:19], v[162:165], v[206:209], v[16:19]
	v_mfma_f32_16x16x32_bf16 v[12:15], v[154:157], v[214:217], v[12:15]
	v_mfma_f32_16x16x32_bf16 v[8:11], v[162:165], v[214:217], v[8:11]
	v_mfma_f32_16x16x32_bf16 v[4:7], v[154:157], v[222:225], v[4:7]
	v_mfma_f32_16x16x32_bf16 v[0:3], v[162:165], v[222:225], v[0:3]
	v_mfma_f32_16x16x32_bf16 v[28:31], v[158:161], v[202:205], v[28:31]
	v_mfma_f32_16x16x32_bf16 v[24:27], v[194:197], v[202:205], v[24:27]
	v_mfma_f32_16x16x32_bf16 v[20:23], v[158:161], v[210:213], v[20:23]
	v_mfma_f32_16x16x32_bf16 v[16:19], v[194:197], v[210:213], v[16:19]
	v_mfma_f32_16x16x32_bf16 v[12:15], v[158:161], v[218:221], v[12:15]
	v_mfma_f32_16x16x32_bf16 v[8:11], v[194:197], v[218:221], v[8:11]
	v_mfma_f32_16x16x32_bf16 v[4:7], v[158:161], v[226:229], v[4:7]
	v_mfma_f32_16x16x32_bf16 v[0:3], v[194:197], v[226:229], v[0:3]
	s_setprio 0
	s_barrier
	v_or_b32_e32 v138, 0x18000, v136
	v_add_u32_e32 v142, 0x18400, v136
	v_add_u32_e32 v146, 0x18800, v136
	v_add_u32_e32 v150, 0x18c00, v136
	v_or_b32_e32 v154, 0x1c000, v136
	v_add_u32_e32 v158, 0x1c400, v136
	v_add_u32_e32 v162, 0x1c800, v136
	ds_read_b128 v[138:141], v138
	ds_read_b128 v[142:145], v142
	ds_read_b128 v[146:149], v146
	ds_read_b128 v[150:153], v150
	ds_read_b128 v[154:157], v154
	ds_read_b128 v[158:161], v158
	v_add_u32_e32 v180, 0x1cc00, v136
	ds_read_b128 v[162:165], v162
	ds_read_b128 v[194:197], v180
	s_add_u32 s26, s26, 0x40000
	s_addc_u32 s27, s27, 0
	s_mov_b32 m0, s49
	v_lshl_add_u64 v[236:237], s[26:27], 0, v[168:169]
	ds_read_b128 v[198:201], v137 offset:32768
	ds_read_b128 v[202:205], v137 offset:33792
	ds_read_b128 v[206:209], v137 offset:34816
	ds_read_b128 v[210:213], v137 offset:35840
	ds_read_b128 v[214:217], v137 offset:36864
	ds_read_b128 v[218:221], v137 offset:37888
	ds_read_b128 v[222:225], v137 offset:38912
	ds_read_b128 v[226:229], v137 offset:39936
	v_lshl_add_u64 v[236:237], s[26:27], 0, v[128:129]
	s_mov_b32 m0, s54
	s_nop 0
	s_waitcnt vmcnt(0)
	s_waitcnt lgkmcnt(0)
	s_barrier
	s_setprio 1
	s_waitcnt lgkmcnt(0)
	v_mfma_f32_16x16x32_bf16 v[124:127], v[138:141], v[198:201], v[124:127]
	v_mfma_f32_16x16x32_bf16 v[120:123], v[146:149], v[198:201], v[120:123]
	v_mfma_f32_16x16x32_bf16 v[116:119], v[138:141], v[206:209], v[116:119]
	v_mfma_f32_16x16x32_bf16 v[112:115], v[146:149], v[206:209], v[112:115]
	v_mfma_f32_16x16x32_bf16 v[108:111], v[138:141], v[214:217], v[108:111]
	v_mfma_f32_16x16x32_bf16 v[104:107], v[146:149], v[214:217], v[104:107]
	v_mfma_f32_16x16x32_bf16 v[100:103], v[138:141], v[222:225], v[100:103]
	v_mfma_f32_16x16x32_bf16 v[96:99], v[146:149], v[222:225], v[96:99]
	v_mfma_f32_16x16x32_bf16 v[124:127], v[142:145], v[202:205], v[124:127]
	v_mfma_f32_16x16x32_bf16 v[120:123], v[150:153], v[202:205], v[120:123]
	v_mfma_f32_16x16x32_bf16 v[116:119], v[142:145], v[210:213], v[116:119]
	v_mfma_f32_16x16x32_bf16 v[112:115], v[150:153], v[210:213], v[112:115]
	v_mfma_f32_16x16x32_bf16 v[108:111], v[142:145], v[218:221], v[108:111]
	v_mfma_f32_16x16x32_bf16 v[104:107], v[150:153], v[218:221], v[104:107]
	v_mfma_f32_16x16x32_bf16 v[100:103], v[142:145], v[226:229], v[100:103]
	v_mfma_f32_16x16x32_bf16 v[96:99], v[150:153], v[226:229], v[96:99]
	s_setprio 0
	s_setprio 1
	v_mfma_f32_16x16x32_bf16 v[92:95], v[154:157], v[198:201], v[92:95]
	v_mfma_f32_16x16x32_bf16 v[88:91], v[162:165], v[198:201], v[88:91]
	v_mfma_f32_16x16x32_bf16 v[84:87], v[154:157], v[206:209], v[84:87]
	v_mfma_f32_16x16x32_bf16 v[80:83], v[162:165], v[206:209], v[80:83]
	v_mfma_f32_16x16x32_bf16 v[76:79], v[154:157], v[214:217], v[76:79]
	v_mfma_f32_16x16x32_bf16 v[72:75], v[162:165], v[214:217], v[72:75]
	v_mfma_f32_16x16x32_bf16 v[68:71], v[154:157], v[222:225], v[68:71]
	v_mfma_f32_16x16x32_bf16 v[64:67], v[162:165], v[222:225], v[64:67]
	v_mfma_f32_16x16x32_bf16 v[92:95], v[158:161], v[202:205], v[92:95]
	v_mfma_f32_16x16x32_bf16 v[88:91], v[194:197], v[202:205], v[88:91]
	v_mfma_f32_16x16x32_bf16 v[84:87], v[158:161], v[210:213], v[84:87]
	v_mfma_f32_16x16x32_bf16 v[80:83], v[194:197], v[210:213], v[80:83]
	v_mfma_f32_16x16x32_bf16 v[76:79], v[158:161], v[218:221], v[76:79]
	v_mfma_f32_16x16x32_bf16 v[72:75], v[194:197], v[218:221], v[72:75]
	v_mfma_f32_16x16x32_bf16 v[68:71], v[158:161], v[226:229], v[68:71]
	v_mfma_f32_16x16x32_bf16 v[64:67], v[194:197], v[226:229], v[64:67]
	s_setprio 0
	s_barrier
	s_mov_b32 m0, s56
	v_lshl_add_u64 v[166:167], v[166:167], 0, s[34:35]
	s_add_u32 s14, s14, 0x40080
	ds_read_b128 v[198:201], v137 offset:49152
	ds_read_b128 v[202:205], v137 offset:50176
	ds_read_b128 v[206:209], v137 offset:51200
	ds_read_b128 v[210:213], v137 offset:52224
	ds_read_b128 v[214:217], v137 offset:53248
	ds_read_b128 v[218:221], v137 offset:54272
	ds_read_b128 v[222:225], v137 offset:55296
	ds_read_b128 v[226:229], v137 offset:56320
	v_lshl_add_u64 v[166:167], v[230:231], 0, s[34:35]
	s_mov_b32 m0, s85
	s_addc_u32 s15, s15, 0
	v_lshl_add_u64 v[166:167], s[14:15], 0, v[168:169]
	s_mov_b32 m0, s90
	s_nop 0
	v_lshl_add_u64 v[166:167], s[14:15], 0, v[128:129]
	s_mov_b32 m0, s24
	s_nop 0
	v_lshl_add_u64 v[166:167], v[232:233], 0, s[34:35]
	s_mov_b32 m0, s86
	s_nop 0
	v_lshl_add_u64 v[166:167], v[234:235], 0, s[34:35]
	s_mov_b32 m0, s87
	s_nop 0
	s_waitcnt vmcnt(0)
	s_waitcnt lgkmcnt(0)
	s_barrier
	s_setprio 1
	s_waitcnt lgkmcnt(0)
	v_mfma_f32_16x16x32_bf16 v[60:63], v[138:141], v[198:201], v[60:63]
	v_mfma_f32_16x16x32_bf16 v[56:59], v[146:149], v[198:201], v[56:59]
	v_mfma_f32_16x16x32_bf16 v[52:55], v[138:141], v[206:209], v[52:55]
	v_mfma_f32_16x16x32_bf16 v[48:51], v[146:149], v[206:209], v[48:51]
	v_mfma_f32_16x16x32_bf16 v[44:47], v[138:141], v[214:217], v[44:47]
	v_mfma_f32_16x16x32_bf16 v[40:43], v[146:149], v[214:217], v[40:43]
	v_mfma_f32_16x16x32_bf16 v[36:39], v[138:141], v[222:225], v[36:39]
	v_mfma_f32_16x16x32_bf16 v[32:35], v[146:149], v[222:225], v[32:35]
	v_mfma_f32_16x16x32_bf16 v[60:63], v[142:145], v[202:205], v[60:63]
	v_mfma_f32_16x16x32_bf16 v[56:59], v[150:153], v[202:205], v[56:59]
	v_mfma_f32_16x16x32_bf16 v[52:55], v[142:145], v[210:213], v[52:55]
	v_mfma_f32_16x16x32_bf16 v[48:51], v[150:153], v[210:213], v[48:51]
	v_mfma_f32_16x16x32_bf16 v[44:47], v[142:145], v[218:221], v[44:47]
	v_mfma_f32_16x16x32_bf16 v[40:43], v[150:153], v[218:221], v[40:43]
	v_mfma_f32_16x16x32_bf16 v[36:39], v[142:145], v[226:229], v[36:39]
	v_mfma_f32_16x16x32_bf16 v[32:35], v[150:153], v[226:229], v[32:35]
	s_setprio 0
	s_setprio 1
	v_mfma_f32_16x16x32_bf16 v[28:31], v[154:157], v[198:201], v[28:31]
	v_mfma_f32_16x16x32_bf16 v[24:27], v[162:165], v[198:201], v[24:27]
	v_mfma_f32_16x16x32_bf16 v[20:23], v[154:157], v[206:209], v[20:23]
	v_mfma_f32_16x16x32_bf16 v[16:19], v[162:165], v[206:209], v[16:19]
	v_mfma_f32_16x16x32_bf16 v[12:15], v[154:157], v[214:217], v[12:15]
	v_mfma_f32_16x16x32_bf16 v[8:11], v[162:165], v[214:217], v[8:11]
	v_mfma_f32_16x16x32_bf16 v[4:7], v[154:157], v[222:225], v[4:7]
	v_mfma_f32_16x16x32_bf16 v[0:3], v[162:165], v[222:225], v[0:3]
	v_mfma_f32_16x16x32_bf16 v[28:31], v[158:161], v[202:205], v[28:31]
	v_mfma_f32_16x16x32_bf16 v[24:27], v[194:197], v[202:205], v[24:27]
	v_mfma_f32_16x16x32_bf16 v[20:23], v[158:161], v[210:213], v[20:23]
	v_mfma_f32_16x16x32_bf16 v[16:19], v[194:197], v[210:213], v[16:19]
	v_mfma_f32_16x16x32_bf16 v[12:15], v[158:161], v[218:221], v[12:15]
	v_mfma_f32_16x16x32_bf16 v[8:11], v[194:197], v[218:221], v[8:11]
	v_mfma_f32_16x16x32_bf16 v[4:7], v[158:161], v[226:229], v[4:7]
	v_mfma_f32_16x16x32_bf16 v[0:3], v[194:197], v[226:229], v[0:3]
	s_setprio 0
	s_barrier
	s_add_i32 s94, s94, 2
	s_add_u32 s44, s44, 0x100
	s_addc_u32 s45, s45, 0
	s_cmp_lt_u32 s94, 14
	s_waitcnt vmcnt(0)
	s_cmpk_gt_u32 s5, 0xff
	s_cbranch_scc1 .LBB0_213
	s_barrier
